# stack: GEMM prologue K-tile loads merged, GEMV early wait removed, P7 O loads up front, P2b rope loads up front, DPP/permlane wave sums instead of ds_bpermute
# speedup vs baseline: 1.0093x; 1.0024x over previous
; __device__ __forceinline__ float silu_f(float v) { return v * __builtin_amdgcn_rcpf(1.0f + __expf(-v)); }
; __device__ __forceinline__ void p0_prologue(const Params& P, LAS unsigned char* lds, int G) {
;     ...
;     for (int it = gw; it < 48 * KS_ADA; it += NGW) {
;         const int nc = it % 48, ks = it / 48, n0 = nc * 256 + lane * 4;
;         f32x4 a0 = {0.f, 0.f, 0.f, 0.f}, a1 = {0.f, 0.f, 0.f, 0.f};
; #pragma unroll 16
;         for (int kk = 0; kk < 128; ++kk) { const int k = ks * 128 + kk; const f32x4 w = __builtin_nontemporal_load((const f32x4*)(P.w_ada + (size_t)k * NADA + n0));
;             const float s0 = silu_f(P.c[k]), s1 = silu_f(P.c[DM + k]); a0 += w * s0; a1 += w * s1; }
.LBB0_8:
	v_add_co_u32_e64 v24, s[4:5], s25, v16
	v_add_co_u32_e32 v20, vcc, 0xfff4c000, v16
	s_nop 0
	v_addc_co_u32_e64 v25, s[4:5], -1, v17, s[4:5]
	v_add_co_u32_e64 v26, s[4:5], s26, v16
	v_lshl_add_u64 v[22:23], v[18:19], 0, s[18:19]
	s_nop 0
	v_addc_co_u32_e64 v27, s[4:5], -1, v17, s[4:5]
	v_add_co_u32_e64 v28, s[4:5], s27, v16
	v_addc_co_u32_e32 v21, vcc, -1, v17, vcc
	s_nop 0
	v_addc_co_u32_e64 v29, s[4:5], -1, v17, s[4:5]
	v_add_co_u32_e64 v30, s[4:5], s28, v16
	global_load_dwordx4 v[56:59], v[22:23], off
	s_nop 0
	v_addc_co_u32_e64 v31, s[4:5], -1, v17, s[4:5]
	v_add_co_u32_e64 v32, s[4:5], s29, v16
	v_add_co_u32_e32 v116, vcc, s24, v22
	s_nop 0
	v_addc_co_u32_e64 v33, s[4:5], -1, v17, s[4:5]
	v_add_co_u32_e64 v34, s[4:5], s30, v16
	v_lshl_add_u64 v[114:115], v[22:23], 0, s[14:15]
	s_nop 0
	v_addc_co_u32_e64 v35, s[4:5], -1, v17, s[4:5]
	v_add_co_u32_e64 v36, s[4:5], s31, v16
	v_addc_co_u32_e32 v117, vcc, 0, v23, vcc
	s_nop 0
	v_addc_co_u32_e64 v37, s[4:5], -1, v17, s[4:5]
	v_add_co_u32_e64 v38, s[4:5], s33, v16
	global_load_dwordx4 v[10:13], v[16:17], off nt
	s_nop 0
	v_addc_co_u32_e64 v39, s[4:5], -1, v17, s[4:5]
	v_add_co_u32_e64 v40, s[4:5], s34, v16
	s_add_u32 s18, s18, 64
	s_nop 0
	v_addc_co_u32_e64 v41, s[4:5], -1, v17, s[4:5]
	v_add_co_u32_e64 v42, s[4:5], s35, v16
	s_addc_u32 s19, s19, 0
	s_nop 0
	v_addc_co_u32_e64 v43, s[4:5], -1, v17, s[4:5]
	v_add_co_u32_e64 v44, s[4:5], s36, v16
	s_cmpk_eq_i32 s18, 0x200
	s_nop 0
	v_addc_co_u32_e64 v45, s[4:5], -1, v17, s[4:5]
	v_add_co_u32_e64 v46, s[4:5], s37, v16
	v_addc_co_u32_e64 v47, s[4:5], -1, v17, s[4:5]
	v_add_co_u32_e64 v48, s[4:5], s38, v16
	s_nop 0
	v_addc_co_u32_e64 v49, s[4:5], -1, v17, s[4:5]
	v_add_co_u32_e64 v50, s[4:5], s39, v16
	s_nop 0
	v_addc_co_u32_e64 v51, s[4:5], -1, v17, s[4:5]
	global_load_dwordx4 v[60:63], v[24:25], off nt
	s_nop 0
	global_load_dwordx4 v[24:27], v[26:27], off nt
	s_nop 0
	global_load_dwordx4 v[64:67], v[22:23], off offset:16
	global_load_dwordx4 v[68:71], v[22:23], off offset:48
	global_load_dwordx4 v[72:75], v[22:23], off offset:32
	global_load_dwordx4 v[76:79], v[28:29], off nt
	s_nop 0
	global_load_dwordx4 v[28:31], v[30:31], off nt
	s_nop 0
	global_load_dwordx4 v[80:83], v[32:33], off nt
	s_nop 0
	global_load_dwordx4 v[32:35], v[34:35], off nt
	s_nop 0
	global_load_dwordx4 v[84:87], v[36:37], off nt
	s_nop 0
	global_load_dwordx4 v[36:39], v[38:39], off nt
	s_nop 0
	global_load_dwordx4 v[90:93], v[40:41], off nt
	s_nop 0
	global_load_dwordx4 v[40:43], v[42:43], off nt
	s_nop 0
	global_load_dwordx4 v[94:97], v[44:45], off nt
	s_nop 0
	global_load_dwordx4 v[44:47], v[46:47], off nt
	s_nop 0
	global_load_dwordx4 v[98:101], v[48:49], off nt
	s_nop 0
	global_load_dwordx4 v[48:51], v[50:51], off nt
	s_nop 0
	global_load_dwordx4 v[102:105], v[114:115], off offset:16
	global_load_dwordx4 v[106:109], v[114:115], off offset:32
	global_load_dwordx4 v[110:113], v[20:21], off nt
	s_nop 0
	global_load_dwordx4 v[20:23], v[116:117], off
	s_nop 0
	global_load_dwordx4 v[114:117], v[114:115], off offset:48
	s_waitcnt vmcnt(23)
	v_mul_f32_e32 v55, 0xbfb8aa3b, v56
	v_mul_f32_e32 v118, 0xbfb8aa3b, v58
	v_mul_f32_e32 v89, 0xbfb8aa3b, v57
	v_exp_f32_e32 v55, v55
	v_exp_f32_e32 v118, v118
	v_mul_f32_e32 v119, 0xbfb8aa3b, v59
	v_exp_f32_e32 v89, v89
	v_exp_f32_e32 v119, v119
	v_add_f32_e32 v55, 1.0, v55
	v_add_f32_e32 v118, 1.0, v118
	v_add_f32_e32 v89, 1.0, v89
	v_rcp_f32_e32 v55, v55
	v_rcp_f32_e32 v148, v118
	v_add_f32_e32 v119, 1.0, v119
	v_rcp_f32_e32 v89, v89
	v_rcp_f32_e32 v119, v119
	v_mul_f32_e32 v56, v56, v55
	v_mul_f32_e32 v58, v58, v148
	v_lshl_add_u64 v[16:17], v[16:17], 0, s[16:17]
	s_waitcnt vmcnt(19)
	v_mul_f32_e32 v122, 0xbfb8aa3b, v66
	s_waitcnt vmcnt(18)
	v_mul_f32_e32 v128, 0xbfb8aa3b, v68
	s_waitcnt vmcnt(17)
	v_mul_f32_e32 v124, 0xbfb8aa3b, v72
	v_mul_f32_e32 v126, 0xbfb8aa3b, v74
	v_mul_f32_e32 v120, 0xbfb8aa3b, v64
	v_mul_f32_e32 v130, 0xbfb8aa3b, v70
	v_exp_f32_e32 v122, v122
	v_exp_f32_e32 v124, v124
	v_exp_f32_e32 v126, v126
	v_exp_f32_e32 v128, v128
	v_exp_f32_e32 v120, v120
	v_exp_f32_e32 v130, v130
	v_mul_f32_e32 v121, 0xbfb8aa3b, v65
	s_waitcnt vmcnt(4)
	v_mul_f32_e32 v132, 0xbfb8aa3b, v102
	v_mul_f32_e32 v134, 0xbfb8aa3b, v104
	s_waitcnt vmcnt(3)
	v_mul_f32_e32 v136, 0xbfb8aa3b, v106
	v_mul_f32_e32 v138, 0xbfb8aa3b, v108
	s_waitcnt vmcnt(1)
	v_mul_f32_e32 v140, 0xbfb8aa3b, v20
	v_mul_f32_e32 v133, 0xbfb8aa3b, v103
	v_mul_f32_e32 v135, 0xbfb8aa3b, v105
	v_mul_f32_e32 v137, 0xbfb8aa3b, v107
	v_mul_f32_e32 v139, 0xbfb8aa3b, v109
	v_mul_f32_e32 v141, 0xbfb8aa3b, v21
	v_mul_f32_e32 v142, 0xbfb8aa3b, v22
	v_exp_f32_e32 v132, v132
	v_exp_f32_e32 v134, v134
	v_exp_f32_e32 v136, v136
	v_exp_f32_e32 v138, v138
	s_waitcnt vmcnt(0)
; __device__ __forceinline__ float silu_f(float v) { return v * __builtin_amdgcn_rcpf(1.0f + __expf(-v)); }
; __device__ __forceinline__ void p0_prologue(const Params& P, LAS unsigned char* lds, int G) {
;     ...
;         for (int kk = 0; kk < 128; ++kk) { const int k = ks * 128 + kk; const f32x4 w = __builtin_nontemporal_load((const f32x4*)(P.w_ada + (size_t)k * NADA + n0));
;             const float s0 = silu_f(P.c[k]), s1 = silu_f(P.c[DM + k]); a0 += w * s0; a1 += w * s1; }
	v_mul_f32_e32 v144, 0xbfb8aa3b, v114
	v_exp_f32_e32 v140, v140
	v_mul_f32_e32 v143, 0xbfb8aa3b, v23
	v_exp_f32_e32 v133, v133
	v_exp_f32_e32 v135, v135
	v_exp_f32_e32 v137, v137
	v_exp_f32_e32 v139, v139
	v_mul_f32_e32 v145, 0xbfb8aa3b, v115
	v_exp_f32_e32 v141, v141
	v_exp_f32_e32 v142, v142
	v_exp_f32_e32 v144, v144
	v_exp_f32_e32 v143, v143
	v_exp_f32_e32 v145, v145
	v_add_f32_e32 v122, 1.0, v122
	v_add_f32_e32 v124, 1.0, v124
	v_add_f32_e32 v126, 1.0, v126
	v_add_f32_e32 v128, 1.0, v128
	v_exp_f32_e32 v121, v121
	v_mul_f32_e32 v146, 0xbfb8aa3b, v116
	v_add_f32_e32 v120, 1.0, v120
	v_add_f32_e32 v130, 1.0, v130
	v_add_f32_e32 v118, 1.0, v132
	v_rcp_f32_e32 v132, v122
	v_add_f32_e32 v122, 1.0, v134
	v_rcp_f32_e32 v134, v124
	v_add_f32_e32 v124, 1.0, v136
	v_rcp_f32_e32 v136, v126
	v_add_f32_e32 v126, 1.0, v138
	v_rcp_f32_e32 v138, v128
	v_add_f32_e32 v128, 1.0, v140
	v_mul_f32_e32 v123, 0xbfb8aa3b, v67
	v_exp_f32_e32 v146, v146
	v_rcp_f32_e32 v149, v120
	v_add_f32_e32 v120, 1.0, v133
	v_add_f32_e32 v133, 1.0, v135
	v_add_f32_e32 v135, 1.0, v137
	v_add_f32_e32 v137, 1.0, v139
	v_rcp_f32_e32 v139, v130
	v_add_f32_e32 v130, 1.0, v141
	v_add_f32_e32 v140, 1.0, v142
	v_rcp_f32_e32 v142, v118
	v_add_f32_e32 v118, 1.0, v144
	v_rcp_f32_e32 v144, v128
	v_exp_f32_e32 v123, v123
	v_add_f32_e32 v141, 1.0, v143
	v_rcp_f32_e32 v143, v120
	v_add_f32_e32 v120, 1.0, v145
	v_rcp_f32_e32 v145, v130
	v_mul_f32_e32 v125, 0xbfb8aa3b, v73
	v_mul_f32_e32 v147, 0xbfb8aa3b, v117
	v_rcp_f32_e32 v140, v140
	v_exp_f32_e32 v125, v125
	v_exp_f32_e32 v147, v147
	v_add_f32_e32 v121, 1.0, v121
	v_rcp_f32_e32 v141, v141
	v_mul_f32_e32 v127, 0xbfb8aa3b, v75
	v_rcp_f32_e32 v121, v121
	v_rcp_f32_e32 v150, v122
	v_add_f32_e32 v122, 1.0, v146
	v_rcp_f32_e32 v146, v118
	v_mul_f32_e32 v118, v57, v89
	v_pk_fma_f32 v[6:7], v[110:111], v[56:57], v[6:7] op_sel_hi:[1,0,1]
	v_pk_fma_f32 v[8:9], v[112:113], v[56:57], v[8:9] op_sel_hi:[1,0,1]
	v_mul_f32_e32 v20, v20, v144
	v_exp_f32_e32 v127, v127
	v_add_f32_e32 v123, 1.0, v123
	v_pk_fma_f32 v[8:9], v[62:63], v[118:119], v[8:9] op_sel_hi:[1,0,1]
	v_pk_fma_f32 v[6:7], v[60:61], v[118:119], v[6:7] op_sel_hi:[1,0,1]
	v_mul_f32_e32 v118, v21, v145
	v_pk_fma_f32 v[4:5], v[112:113], v[20:21], v[4:5] op_sel_hi:[1,0,1]
	v_pk_fma_f32 v[2:3], v[110:111], v[20:21], v[2:3] op_sel_hi:[1,0,1]
	v_mul_f32_e32 v129, 0xbfb8aa3b, v69
	v_rcp_f32_e32 v123, v123
	v_mul_f32_e32 v22, v22, v140
	v_pk_fma_f32 v[4:5], v[62:63], v[118:119], v[4:5] op_sel_hi:[1,0,1]
	v_pk_fma_f32 v[2:3], v[60:61], v[118:119], v[2:3] op_sel_hi:[1,0,1]
	v_exp_f32_e32 v129, v129
	v_add_f32_e32 v125, 1.0, v125
	v_rcp_f32_e32 v133, v133
	v_rcp_f32_e32 v151, v124
	v_add_f32_e32 v124, 1.0, v147
	v_rcp_f32_e32 v147, v120
	v_mul_f32_e32 v120, v59, v119
	v_mul_f32_e32 v140, v23, v141
	v_pk_fma_f32 v[8:9], v[26:27], v[58:59], v[8:9] op_sel_hi:[1,0,1]
	v_pk_fma_f32 v[6:7], v[24:25], v[58:59], v[6:7] op_sel_hi:[1,0,1]
	v_pk_fma_f32 v[2:3], v[24:25], v[22:23], v[2:3] op_sel_hi:[1,0,1]
	v_pk_fma_f32 v[4:5], v[26:27], v[22:23], v[4:5] op_sel_hi:[1,0,1]
	v_mul_f32_e32 v131, 0xbfb8aa3b, v71
	v_rcp_f32_e32 v125, v125
	v_rcp_f32_e32 v135, v135
	v_mul_f32_e32 v64, v64, v149
	v_mul_f32_e32 v56, v102, v142
	v_pk_fma_f32 v[8:9], v[78:79], v[120:121], v[8:9] op_sel_hi:[1,0,1]
	v_pk_fma_f32 v[6:7], v[76:77], v[120:121], v[6:7] op_sel_hi:[1,0,1]
	v_pk_fma_f32 v[4:5], v[78:79], v[140:141], v[4:5] op_sel_hi:[1,0,1]
	v_pk_fma_f32 v[2:3], v[76:77], v[140:141], v[2:3] op_sel_hi:[1,0,1]
	v_exp_f32_e32 v131, v131
	v_add_f32_e32 v127, 1.0, v127
	v_rcp_f32_e32 v153, v122
	v_mul_f32_e32 v122, v65, v121
	v_mul_f32_e32 v102, v103, v143
	v_pk_fma_f32 v[8:9], v[30:31], v[64:65], v[8:9] op_sel_hi:[1,0,1]
	v_pk_fma_f32 v[6:7], v[28:29], v[64:65], v[6:7] op_sel_hi:[1,0,1]
	v_pk_fma_f32 v[2:3], v[28:29], v[56:57], v[2:3] op_sel_hi:[1,0,1]
	v_pk_fma_f32 v[4:5], v[30:31], v[56:57], v[4:5] op_sel_hi:[1,0,1]
	v_rcp_f32_e32 v127, v127
	v_rcp_f32_e32 v152, v126
	v_rcp_f32_e32 v137, v137
	v_mul_f32_e32 v66, v66, v132
	v_mul_f32_e32 v104, v104, v150
	v_pk_fma_f32 v[8:9], v[82:83], v[122:123], v[8:9] op_sel_hi:[1,0,1]
	v_pk_fma_f32 v[6:7], v[80:81], v[122:123], v[6:7] op_sel_hi:[1,0,1]
; __device__ __forceinline__ float silu_f(float v) { return v * __builtin_amdgcn_rcpf(1.0f + __expf(-v)); }
; __device__ __forceinline__ void p0_prologue(const Params& P, LAS unsigned char* lds, int G) {
;     ...
;         for (int kk = 0; kk < 128; ++kk) { const int k = ks * 128 + kk; const f32x4 w = __builtin_nontemporal_load((const f32x4*)(P.w_ada + (size_t)k * NADA + n0));
;             const float s0 = silu_f(P.c[k]), s1 = silu_f(P.c[DM + k]); a0 += w * s0; a1 += w * s1; }
;         *(f32x4*)(adap + (size_t)(ks * 2 + 0) * NADA + n0) = a0; *(f32x4*)(adap + (size_t)(ks * 2 + 1) * NADA + n0) = a1;
	v_pk_fma_f32 v[4:5], v[82:83], v[102:103], v[4:5] op_sel_hi:[1,0,1]
	v_pk_fma_f32 v[2:3], v[80:81], v[102:103], v[2:3] op_sel_hi:[1,0,1]
	v_add_f32_e32 v129, 1.0, v129
	v_rcp_f32_e32 v154, v124
	v_mul_f32_e32 v124, v67, v123
	v_mul_f32_e32 v72, v72, v134
	v_mul_f32_e32 v134, v105, v133
	v_pk_fma_f32 v[8:9], v[34:35], v[66:67], v[8:9] op_sel_hi:[1,0,1]
	v_pk_fma_f32 v[6:7], v[32:33], v[66:67], v[6:7] op_sel_hi:[1,0,1]
	v_pk_fma_f32 v[2:3], v[32:33], v[104:105], v[2:3] op_sel_hi:[1,0,1]
	v_pk_fma_f32 v[4:5], v[34:35], v[104:105], v[4:5] op_sel_hi:[1,0,1]
	v_rcp_f32_e32 v129, v129
	v_mul_f32_e32 v106, v106, v151
	v_pk_fma_f32 v[8:9], v[86:87], v[124:125], v[8:9] op_sel_hi:[1,0,1]
	v_pk_fma_f32 v[6:7], v[84:85], v[124:125], v[6:7] op_sel_hi:[1,0,1]
	v_pk_fma_f32 v[4:5], v[86:87], v[134:135], v[4:5] op_sel_hi:[1,0,1]
	v_pk_fma_f32 v[2:3], v[84:85], v[134:135], v[2:3] op_sel_hi:[1,0,1]
	v_add_f32_e32 v131, 1.0, v131
	v_mul_f32_e32 v126, v73, v125
	v_mul_f32_e32 v74, v74, v136
	v_mul_f32_e32 v136, v107, v135
	v_pk_fma_f32 v[8:9], v[38:39], v[72:73], v[8:9] op_sel_hi:[1,0,1]
	v_pk_fma_f32 v[6:7], v[36:37], v[72:73], v[6:7] op_sel_hi:[1,0,1]
	v_pk_fma_f32 v[2:3], v[36:37], v[106:107], v[2:3] op_sel_hi:[1,0,1]
	v_pk_fma_f32 v[4:5], v[38:39], v[106:107], v[4:5] op_sel_hi:[1,0,1]
	v_rcp_f32_e32 v131, v131
	v_mul_f32_e32 v108, v108, v152
	v_pk_fma_f32 v[8:9], v[92:93], v[126:127], v[8:9] op_sel_hi:[1,0,1]
	v_pk_fma_f32 v[6:7], v[90:91], v[126:127], v[6:7] op_sel_hi:[1,0,1]
	v_pk_fma_f32 v[4:5], v[92:93], v[136:137], v[4:5] op_sel_hi:[1,0,1]
	v_pk_fma_f32 v[2:3], v[90:91], v[136:137], v[2:3] op_sel_hi:[1,0,1]
	v_mul_f32_e32 v128, v75, v127
	v_mul_f32_e32 v68, v68, v138
	v_mul_f32_e32 v138, v109, v137
	v_pk_fma_f32 v[8:9], v[42:43], v[74:75], v[8:9] op_sel_hi:[1,0,1]
	v_pk_fma_f32 v[6:7], v[40:41], v[74:75], v[6:7] op_sel_hi:[1,0,1]
	v_pk_fma_f32 v[2:3], v[40:41], v[108:109], v[2:3] op_sel_hi:[1,0,1]
	v_pk_fma_f32 v[4:5], v[42:43], v[108:109], v[4:5] op_sel_hi:[1,0,1]
	v_mul_f32_e32 v114, v114, v146
	v_pk_fma_f32 v[8:9], v[96:97], v[128:129], v[8:9] op_sel_hi:[1,0,1]
	v_pk_fma_f32 v[6:7], v[94:95], v[128:129], v[6:7] op_sel_hi:[1,0,1]
	v_pk_fma_f32 v[4:5], v[96:97], v[138:139], v[4:5] op_sel_hi:[1,0,1]
	v_pk_fma_f32 v[2:3], v[94:95], v[138:139], v[2:3] op_sel_hi:[1,0,1]
	v_mul_f32_e32 v130, v69, v129
	v_mul_f32_e32 v142, v115, v147
	v_pk_fma_f32 v[8:9], v[46:47], v[68:69], v[8:9] op_sel_hi:[1,0,1]
	v_pk_fma_f32 v[6:7], v[44:45], v[68:69], v[6:7] op_sel_hi:[1,0,1]
	v_pk_fma_f32 v[2:3], v[44:45], v[114:115], v[2:3] op_sel_hi:[1,0,1]
	v_pk_fma_f32 v[4:5], v[46:47], v[114:115], v[4:5] op_sel_hi:[1,0,1]
	v_mul_f32_e32 v70, v70, v139
	v_mul_f32_e32 v116, v116, v153
	v_pk_fma_f32 v[8:9], v[100:101], v[130:131], v[8:9] op_sel_hi:[1,0,1]
	v_pk_fma_f32 v[6:7], v[98:99], v[130:131], v[6:7] op_sel_hi:[1,0,1]
	v_pk_fma_f32 v[4:5], v[100:101], v[142:143], v[4:5] op_sel_hi:[1,0,1]
	v_pk_fma_f32 v[2:3], v[98:99], v[142:143], v[2:3] op_sel_hi:[1,0,1]
	v_mul_f32_e32 v132, v71, v131
	v_mul_f32_e32 v144, v117, v154
	v_pk_fma_f32 v[8:9], v[50:51], v[70:71], v[8:9] op_sel_hi:[1,0,1]
	v_pk_fma_f32 v[6:7], v[48:49], v[70:71], v[6:7] op_sel_hi:[1,0,1]
	v_pk_fma_f32 v[2:3], v[48:49], v[116:117], v[2:3] op_sel_hi:[1,0,1]
	v_pk_fma_f32 v[4:5], v[50:51], v[116:117], v[4:5] op_sel_hi:[1,0,1]
	v_pk_fma_f32 v[8:9], v[12:13], v[132:133], v[8:9] op_sel_hi:[1,0,1]
	v_pk_fma_f32 v[6:7], v[10:11], v[132:133], v[6:7] op_sel_hi:[1,0,1]
	v_pk_fma_f32 v[4:5], v[12:13], v[144:145], v[4:5] op_sel_hi:[1,0,1]
	v_pk_fma_f32 v[2:3], v[10:11], v[144:145], v[2:3] op_sel_hi:[1,0,1]
	s_cbranch_scc0 .LBB0_8
	v_lshlrev_b32_e32 v16, 1, v54
	v_mov_b64_e32 v[10:11], s[58:59]
	v_mad_i64_i32 v[12:13], s[4:5], v16, s23, v[10:11]
	v_lshl_add_u64 v[12:13], v[12:13], 0, v[14:15]
	global_store_dwordx4 v[12:13], v[6:9], off
	v_add_u32_e32 v53, s42, v53
	v_cmp_lt_i32_e32 vcc, s40, v53
	v_or_b32_e32 v6, 1, v16
	v_mad_i64_i32 v[6:7], s[4:5], v6, s23, v[10:11]
	v_lshl_add_u64 v[6:7], v[6:7], 0, v[14:15]
	s_or_b64 s[12:13], vcc, s[12:13]
	global_store_dwordx4 v[6:7], v[2:5], off
	s_andn2_b64 exec, exec, s[12:13]
	s_cbranch_execnz .LBB0_7

; __device__ __forceinline__ float wave_sum(float v) {
; #pragma unroll
;     for (int o = 1; o < 64; o <<= 1) v += __shfl_xor(v, o);
;     return v;
; __device__ __forceinline__ void p1_rows(const Params& P, LAS unsigned char* lds, int G) {
;     ...
;         const int b = m >> 13; const f32x4* xr = (const f32x4*)(P.x + (size_t)m * DM) + lane;
;         f32x4 v[8]; float ss = 0.f;
; #pragma unroll
;         for (int j = 0; j < 8; ++j) { v[j] = __builtin_nontemporal_load(xr + 64 * j); ss += (v[j][0] * v[j][0] + v[j][1] * v[j][1]) + (v[j][2] * v[j][2] + v[j][3] * v[j][3]); }
;         const float rstd = rsqrtf(wave_sum(ss) * (1.0f / DM) + RMS_EPS);
.LBB0_168:
	global_load_dwordx4 v[4:7], v[34:35], off offset:-4096 nt
	global_load_dwordx4 v[0:3], v[34:35], off offset:-3072 nt
	global_load_dwordx4 v[8:11], v[34:35], off offset:-2048 nt
	global_load_dwordx4 v[12:15], v[34:35], off offset:1024 nt
	global_load_dwordx4 v[16:19], v[34:35], off nt
	global_load_dwordx4 v[20:23], v[34:35], off offset:-1024 nt
	global_load_dwordx4 v[24:27], v[34:35], off offset:3072 nt
	global_load_dwordx4 v[28:31], v[34:35], off offset:2048 nt
	v_and_b32_e32 v45, 0xffffe000, v32
	v_add_u32_e32 v45, v44, v45
	ds_read_b128 v[46:49], v45
	ds_read_b128 v[50:53], v45 offset:1024
	ds_read_b128 v[54:57], v45 offset:16384
	ds_read_b128 v[58:61], v45 offset:17408
	ds_read_b128 v[62:65], v45 offset:2048
	ds_read_b128 v[66:69], v45 offset:3072
	ds_read_b128 v[70:73], v45 offset:18432
	ds_read_b128 v[74:77], v45 offset:19456
	ds_read_b128 v[78:81], v45 offset:4096
	ds_read_b128 v[82:85], v45 offset:5120
	ds_read_b128 v[86:89], v45 offset:20480
	ds_read_b128 v[90:93], v45 offset:21504
	ds_read_b128 v[94:97], v45 offset:6144
	ds_read_b128 v[98:101], v45 offset:7168
	ds_read_b128 v[102:105], v45 offset:22528
	ds_read_b128 v[106:109], v45 offset:23552
	v_add_u32_e32 v32, s42, v32
	v_cmp_lt_i32_e32 vcc, s13, v32
	s_or_b64 s[10:11], vcc, s[10:11]
	v_lshl_add_u64 v[34:35], v[34:35], 0, s[6:7]
	s_waitcnt vmcnt(7)
	v_mov_b32_e32 v112, v5
	s_waitcnt vmcnt(6)
	v_mov_b32_e32 v113, v1
	s_waitcnt vmcnt(5)
	v_pk_mul_f32 v[114:115], v[10:11], v[10:11]
	v_pk_mul_f32 v[116:117], v[8:9], v[8:9]
	s_waitcnt vmcnt(4)
	v_pk_mul_f32 v[118:119], v[14:15], v[14:15]
	v_pk_mul_f32 v[120:121], v[12:13], v[12:13]
	v_mov_b32_e32 v124, v7
	v_mov_b32_e32 v125, v3
	v_mov_b32_e32 v110, v4
	v_mov_b32_e32 v111, v0
	v_mov_b32_e32 v122, v6
	v_mov_b32_e32 v123, v2
	v_pk_mov_b32 v[134:135], v[116:117], v[114:115] op_sel:[1,0]
	v_mov_b32_e32 v117, v115
	v_pk_mov_b32 v[114:115], v[120:121], v[118:119] op_sel:[1,0]
	v_mov_b32_e32 v121, v119
	v_pk_mul_f32 v[112:113], v[112:113], v[112:113]
	v_pk_mul_f32 v[118:119], v[124:125], v[124:125]
	v_pk_fma_f32 v[110:111], v[110:111], v[110:111], v[112:113]
	v_pk_fma_f32 v[112:113], v[122:123], v[122:123], v[118:119]
	s_waitcnt vmcnt(2)
	v_mul_f32_e32 v126, v21, v21
	v_mul_f32_e32 v128, v23, v23
	v_pk_add_f32 v[116:117], v[134:135], v[116:117]
	v_pk_add_f32 v[110:111], v[110:111], v[112:113]
	v_mul_f32_e32 v45, v16, v16
	v_mul_f32_e32 v133, v18, v18
	v_mul_f32_e32 v136, v19, v19
	v_mul_f32_e32 v139, v17, v17
	v_pk_fma_f32 v[124:125], v[20:21], v[20:21], v[126:127] op_sel_hi:[1,1,0]
	v_pk_fma_f32 v[126:127], v[22:23], v[22:23], v[128:129] op_sel_hi:[1,1,0]
	v_pk_add_f32 v[116:117], v[116:117], v[116:117] op_sel:[0,1] op_sel_hi:[1,0]
	v_pk_add_f32 v[110:111], v[110:111], v[110:111] op_sel:[0,1] op_sel_hi:[1,0]
	v_mov_b32_e32 v125, v133
	v_mov_b32_e32 v127, v136
	v_mov_b32_e32 v117, v139
	v_mov_b32_e32 v111, v45
	v_pk_add_f32 v[112:113], v[124:125], v[126:127]
	v_pk_add_f32 v[110:111], v[110:111], v[116:117]
	s_waitcnt vmcnt(0)
	v_mul_f32_e32 v130, v29, v29
	v_mul_f32_e32 v132, v31, v31
	v_pk_add_f32 v[114:115], v[114:115], v[120:121]
	v_pk_add_f32 v[110:111], v[110:111], v[112:113]
	v_mul_f32_e32 v137, v26, v26
	v_mul_f32_e32 v138, v27, v27
	v_mul_f32_e32 v140, v24, v24
	v_mul_f32_e32 v141, v25, v25
	v_pk_fma_f32 v[128:129], v[28:29], v[28:29], v[130:131] op_sel_hi:[1,1,0]
	v_pk_fma_f32 v[130:131], v[30:31], v[30:31], v[132:133] op_sel_hi:[1,1,0]
	v_pk_add_f32 v[114:115], v[114:115], v[114:115] op_sel:[0,1] op_sel_hi:[1,0]
	v_pk_add_f32 v[110:111], v[110:111], v[110:111] op_sel:[0,1] op_sel_hi:[1,0]
	v_mov_b32_e32 v129, v137
	v_mov_b32_e32 v131, v138
	v_mov_b32_e32 v115, v141
	v_mov_b32_e32 v111, v140
	v_pk_add_f32 v[118:119], v[128:129], v[130:131]
	v_pk_add_f32 v[110:111], v[110:111], v[114:115]
	s_nop 0
	v_pk_add_f32 v[110:111], v[110:111], v[118:119]
	s_nop 0
	v_add_f32_e32 v45, v110, v111
	s_nop 1
	v_add_f32_dpp v45, v45, v45 quad_perm:[1,0,3,2] row_mask:0xf bank_mask:0xf
	s_nop 1
	v_add_f32_dpp v45, v45, v45 quad_perm:[2,3,0,1] row_mask:0xf bank_mask:0xf
	s_nop 1
	v_add_f32_dpp v45, v45, v45 row_half_mirror row_mask:0xf bank_mask:0xf
	s_nop 1
	v_add_f32_dpp v45, v45, v45 row_mirror row_mask:0xf bank_mask:0xf
	v_mov_b32_e32 v110, v45
	s_nop 1
	v_permlane16_swap_b32_e32 v110, v45
	v_add_f32_e32 v45, v45, v110
	v_mov_b32_e32 v110, v45
	s_nop 1
	v_permlane32_swap_b32_e32 v110, v45
	v_add_f32_e32 v45, v45, v110
	s_waitcnt lgkmcnt(0)
; #define LAS __attribute__((address_space(3)))
; __device__ __forceinline__ unsigned pk2(float lo, float hi) { return pg8::cvtpk(lo, hi); }
; __device__ __forceinline__ void p1_rows(const Params& P, LAS unsigned char* lds, int G) {
;     ...
;         const float rstd = rsqrtf(wave_sum(ss) * (1.0f / DM) + RMS_EPS);
;         u32x2* o = (u32x2*)(XN + (size_t)m * DM) + lane;
; #pragma unroll
;         for (int j = 0; j < 8; ++j) { const f32x4 a = *(const LAS f32x4*)(TA + b * DM + 256 * j + 4 * lane), c = *(const LAS f32x4*)(TC + b * DM + 256 * j + 4 * lane);
;             const f32x4 h = v[j] * rstd * a + c; u32x2 w; w.x = pk2(h[0], h[1]); w.y = pk2(h[2], h[3]); o[64 * j] = w; }
	v_fmamk_f32 v45, v45, 0x3a000000, v33
	v_mul_f32_e32 v110, 0x4b800000, v45
	v_cmp_gt_f32_e32 vcc, s12, v45
	s_nop 1
	v_cndmask_b32_e32 v45, v45, v110, vcc
	v_rsq_f32_e32 v45, v45
	s_nop 0
	v_mul_f32_e32 v110, 0x45800000, v45
	v_cndmask_b32_e32 v110, v45, v110, vcc
	v_pk_mul_f32 v[4:5], v[4:5], v[110:111] op_sel_hi:[1,0]
	v_pk_mul_f32 v[6:7], v[6:7], v[110:111] op_sel_hi:[1,0]
	v_pk_mul_f32 v[0:1], v[0:1], v[110:111] op_sel_hi:[1,0]
	v_pk_mul_f32 v[2:3], v[2:3], v[110:111] op_sel_hi:[1,0]
	v_pk_mul_f32 v[8:9], v[8:9], v[110:111] op_sel_hi:[1,0]
	v_pk_mul_f32 v[10:11], v[10:11], v[110:111] op_sel_hi:[1,0]
	v_pk_mul_f32 v[20:21], v[20:21], v[110:111] op_sel_hi:[1,0]
	v_pk_mul_f32 v[22:23], v[22:23], v[110:111] op_sel_hi:[1,0]
	v_pk_mul_f32 v[16:17], v[16:17], v[110:111] op_sel_hi:[1,0]
	v_pk_mul_f32 v[18:19], v[18:19], v[110:111] op_sel_hi:[1,0]
	v_pk_mul_f32 v[12:13], v[12:13], v[110:111] op_sel_hi:[1,0]
	v_pk_mul_f32 v[14:15], v[14:15], v[110:111] op_sel_hi:[1,0]
	v_pk_mul_f32 v[28:29], v[28:29], v[110:111] op_sel_hi:[1,0]
	v_pk_mul_f32 v[30:31], v[30:31], v[110:111] op_sel_hi:[1,0]
	v_pk_mul_f32 v[24:25], v[24:25], v[110:111] op_sel_hi:[1,0]
	v_pk_mul_f32 v[26:27], v[26:27], v[110:111] op_sel_hi:[1,0]
	v_pk_fma_f32 v[6:7], v[48:49], v[6:7], v[56:57]
	v_pk_fma_f32 v[4:5], v[46:47], v[4:5], v[54:55]
	v_pk_fma_f32 v[2:3], v[52:53], v[2:3], v[60:61]
	v_pk_fma_f32 v[0:1], v[50:51], v[0:1], v[58:59]
	v_pk_fma_f32 v[10:11], v[64:65], v[10:11], v[72:73]
	v_pk_fma_f32 v[8:9], v[62:63], v[8:9], v[70:71]
	v_pk_fma_f32 v[22:23], v[68:69], v[22:23], v[76:77]
	v_pk_fma_f32 v[20:21], v[66:67], v[20:21], v[74:75]
	v_pk_fma_f32 v[18:19], v[80:81], v[18:19], v[88:89]
	v_pk_fma_f32 v[16:17], v[78:79], v[16:17], v[86:87]
	v_pk_fma_f32 v[14:15], v[14:15], v[84:85], v[92:93]
	v_pk_fma_f32 v[12:13], v[12:13], v[82:83], v[90:91]
	v_pk_fma_f32 v[30:31], v[30:31], v[96:97], v[104:105]
	v_pk_fma_f32 v[28:29], v[28:29], v[94:95], v[102:103]
	v_pk_fma_f32 v[26:27], v[26:27], v[100:101], v[108:109]
	v_pk_fma_f32 v[24:25], v[24:25], v[98:99], v[106:107]
	v_cvt_pk_bf16_f32 v4, v4, v5
	v_cvt_pk_bf16_f32 v5, v6, v7
	v_cvt_pk_bf16_f32 v0, v0, v1
	v_cvt_pk_bf16_f32 v1, v2, v3
	v_cvt_pk_bf16_f32 v2, v8, v9
	v_cvt_pk_bf16_f32 v3, v10, v11
	v_cvt_pk_bf16_f32 v6, v20, v21
	v_cvt_pk_bf16_f32 v7, v22, v23
	v_cvt_pk_bf16_f32 v8, v16, v17
	v_cvt_pk_bf16_f32 v9, v18, v19
	v_cvt_pk_bf16_f32 v10, v12, v13
	v_cvt_pk_bf16_f32 v11, v14, v15
	v_cvt_pk_bf16_f32 v12, v28, v29
	v_cvt_pk_bf16_f32 v13, v30, v31
	v_cvt_pk_bf16_f32 v14, v24, v25
	v_cvt_pk_bf16_f32 v15, v26, v27
	global_store_dwordx2 v[36:37], v[4:5], off
	global_store_dwordx2 v[36:37], v[0:1], off offset:512
	global_store_dwordx2 v[36:37], v[2:3], off offset:1024
	global_store_dwordx2 v[36:37], v[6:7], off offset:1536
	global_store_dwordx2 v[36:37], v[8:9], off offset:2048
	global_store_dwordx2 v[36:37], v[10:11], off offset:2560
	global_store_dwordx2 v[36:37], v[12:13], off offset:3072
	global_store_dwordx2 v[36:37], v[14:15], off offset:3584
	v_lshl_add_u64 v[36:37], v[36:37], 0, s[8:9]
	s_andn2_b64 exec, exec, s[10:11]
	s_cbranch_execnz .LBB0_168

; #define PG8_STAGE(bufoff, gbase, voff) do { _Pragma("unroll") for (int _i = 0; _i < 2; ++_i) \
;         __builtin_amdgcn_global_load_lds((const unsigned*)((const char*)(gbase) + (voff)[_i]), (PG8_LAS unsigned*)(lds + (bufoff) + ldsw + _i * 8192), 16, 0, 0); } while (0)
; #define PG8_WAIT_V(n) asm volatile("s_waitcnt vmcnt(" #n ")" ::: "memory")
; #define PG8_BAR __builtin_amdgcn_s_barrier()
; template <class Epi, class Sched, bool ALIGN_EPI = false, bool SP2 = false>
; __device__ __forceinline__ void gemm_phase(PG8_LAS unsigned char* lds, const Gemm g, const Sched& S, const Epi& E) {
;     ...
;     if constexpr (SP2) {
;         PG8_STAGE(PG8_SB(0, 0), cB, voffB); PG8_STAGE(PG8_SB(0, 1), cB + hstepB, voffB); PG8_STAGE(PG8_SA(0, 0), cA, voffA); PG8_STAGE(PG8_SA(0, 1), cA + hstepA, voffA);
;         if (wr == 1) PG8_BAR;
;         PG8_WAIT_V(2); PG8_BAR;
;         PG8_STAGE(PG8_SB(1, 0), cB + kstep, voffB); PG8_STAGE(PG8_SA(1, 0), cA + kstep, voffA); PG8_STAGE(PG8_SB(1, 1), cB + hstepB + kstep, voffB);
;         PG8_WAIT_V(6); PG8_BAR;
.LBB0_228:
	s_lshl_b32 s22, s22, 5
	s_and_b32 s39, s22, 0x60
	s_mov_b64 s[22:23], 0x80
	s_add_i32 m0, s43, 0x18000
	v_lshl_add_u64 v[6:7], v[6:7], 0, s[22:23]
	s_lshl_b32 s37, s38, 13
	s_lshl_b32 s44, s39, 7
	global_load_lds_dwordx4 v[6:7], off
	v_lshl_add_u64 v[4:5], v[4:5], 0, s[22:23]
	s_add_i32 m0, s43, 0x1a000
	s_add_i32 s74, s43, 0x8000
	s_add_i32 s75, s43, 0xa000
	global_load_lds_dwordx4 v[4:5], off
	v_lshl_add_u64 v[0:1], v[0:1], 0, s[22:23]
	s_mov_b32 m0, s74
	s_add_u32 s40, s64, 0x80080
	global_load_lds_dwordx4 v[0:1], off
	v_lshl_add_u64 v[0:1], v[2:3], 0, s[22:23]
	s_mov_b32 m0, s75
	s_addc_u32 s41, s65, 0
	global_load_lds_dwordx4 v[0:1], off
	s_add_i32 m0, s43, 0x1c000
	v_lshl_add_u64 v[0:1], s[40:41], 0, v[130:131]
	global_load_lds_dwordx4 v[0:1], off
	v_lshl_add_u64 v[0:1], s[40:41], 0, v[134:135]
	s_add_i32 m0, s43, 0x1e000
	s_cmpk_lt_u32 s27, 0x100
	global_load_lds_dwordx4 v[0:1], off
	s_waitcnt vmcnt(8)
	s_barrier
	v_lshrrev_b32_e32 v1, 1, v8
	v_and_b32_e32 v1, 24, v1
	v_and_b32_e32 v0, 15, v8
	v_lshlrev_b32_e32 v2, 1, v1
	v_lshl_or_b32 v144, s38, 6, v0
	v_lshl_or_b32 v0, v0, 6, v2
	v_lshlrev_b32_e32 v2, 2, v8
	v_and_b32_e32 v2, 32, v2
	v_bitop3_b32 v3, v0, s37, v2 bitop3:0xde
	v_bitop3_b32 v145, v0, s44, v2 bitop3:0xde
	v_lshlrev_b32_e32 v0, 15, v9
	v_and_b32_e32 v0, 0xffff0000, v0
	v_or_b32_e32 v146, s39, v1
	v_lshl_add_u32 v0, v10, 12, v0
	v_and_b32_e32 v1, 1, v9
	v_lshl_or_b32 v0, v1, 6, v0
	v_lshl_add_u32 v136, v11, 1, v0
	v_lshlrev_b32_e32 v0, 15, v12
	v_and_b32_e32 v0, 0xffff0000, v0
	s_waitcnt vmcnt(6)
	v_lshl_add_u32 v0, v13, 12, v0
	v_and_b32_e32 v1, 1, v12
	s_sext_i32_i8 s37, s26
	s_cselect_b64 s[26:27], -1, 0
	v_lshl_or_b32 v0, v1, 6, v0
	s_add_i32 s77, 0, 0x10000
	s_add_i32 s78, 0, 0x14000
	s_ashr_i32 s76, s92, 31
	v_mov_b32_e32 v137, v131
	v_lshl_add_u32 v138, v14, 1, v0
	v_mov_b32_e32 v139, v131
	v_mov_b64_e32 v[140:141], 0x400
	v_mov_b64_e32 v[142:143], 0x3ff
	v_add_u32_e32 v147, s77, v145
	v_add_u32_e32 v148, s78, v145
	v_add_u32_e32 v149, 0, v3
	s_barrier
	s_branch .LBB0_231

; __device__ __forceinline__ float bf2f(unsigned short u) { return __uint_as_float((unsigned)u << 16); }
; __device__ __forceinline__ unsigned short f2bf(float f) { unsigned u = __float_as_uint(f); return (unsigned short)((u + 0x7fffu + ((u >> 16) & 1u)) >> 16); }
; __device__ __forceinline__ unsigned pk2(float lo, float hi) { return pg8::cvtpk(lo, hi); }
; __device__ __forceinline__ void p2b_rows(const Params& P, int G) {
;     ...
;     for (int m = blockIdx.x * 8 + wave; m < M; m += G * 8) {
;         const bf16_t* zr = Z + (size_t)m * ZC;
;         const u32x4 a = *(const u32x4*)(zr + ZO_CQ + 8 * lane); const u32x2 k = *(const u32x2*)(zr + ZO_CKV + 4 * lane);
;         float s1 = 0.f, s2 = 0.f;
; #pragma unroll
;         for (int e = 0; e < 4; ++e) { const float lo = __uint_as_float(a[e] << 16), hi = __uint_as_float(a[e] & 0xffff0000u); s1 += lo * lo + hi * hi; }
; #pragma unroll
;         for (int e = 0; e < 2; ++e) { const float lo = __uint_as_float(k[e] << 16), hi = __uint_as_float(k[e] & 0xffff0000u); s2 += lo * lo + hi * hi; }
;         s1 = wave_sum(s1); s2 = wave_sum(s2);
;         const float r1 = rsqrtf(s1 * (1.0f / 512.0f) + RMS_EPS), r2 = rsqrtf(s2 * (1.0f / 256.0f) + RMS_EPS);
;         { u32x4 w;
; #pragma unroll
;           for (int e = 0; e < 4; ++e) w[e] = pk2(__uint_as_float(a[e] << 16) * r1, __uint_as_float(a[e] & 0xffff0000u) * r1);
;           *(u32x4*)(CQN + (size_t)m * 512 + 8 * lane) = w;
;           u32x2 w2;
; #pragma unroll
;           for (int e = 0; e < 2; ++e) w2[e] = pk2(__uint_as_float(k[e] << 16) * r2, __uint_as_float(k[e] & 0xffff0000u) * r2);
;           *(u32x2*)(CKVN + (size_t)m * 256 + 4 * lane) = w2; }
;         if (lane < 32) { const float x1 = bf2f(zr[ZO_KR + lane]), x2 = bf2f(zr[ZO_KR + 32 + lane]); const float c = cs[(size_t)m * 64 + 2 * lane], s = cs[(size_t)m * 64 + 2 * lane + 1];
;             KR[(size_t)m * 64 + lane] = f2bf(x1 * c - x2 * s); KR[(size_t)m * 64 + 32 + lane] = f2bf(x2 * c + x1 * s); }
.LBB0_300:
	v_lshl_add_u64 v[26:27], v[16:17], 0, v[12:13]
	global_load_dwordx4 v[26:29], v[26:27], off
	v_lshl_add_u64 v[30:31], v[16:17], 0, v[2:3]
	global_load_dwordx2 v[30:31], v[30:31], off offset:1024
	v_lshl_add_u64 v[100:101], v[16:17], 0, v[4:5]
	s_mov_b64 s[4:5], 0x1000
	v_lshl_add_u64 v[102:103], s[58:59], 0, v[6:7]
	v_lshl_add_u64 v[100:101], v[100:101], 0, s[4:5]
	s_mov_b64 s[4:5], 0x300000
	global_load_ushort v104, v[100:101], off offset:3584
	global_load_ushort v105, v[100:101], off offset:3648
	v_lshl_add_u64 v[102:103], v[102:103], 0, s[4:5]
	global_load_dwordx2 v[106:107], v[102:103], off
	s_waitcnt vmcnt(4)
	v_and_b32_e32 v33, 0xffff0000, v29
	v_and_b32_e32 v35, 0xffff0000, v28
	v_lshlrev_b32_e32 v32, 16, v29
	v_lshlrev_b32_e32 v34, 16, v28
	v_mov_b32_e32 v36, v33
	v_mov_b32_e32 v37, v35
	v_mov_b32_e32 v28, v32
	v_mov_b32_e32 v29, v34
	v_pk_mul_f32 v[36:37], v[36:37], v[36:37]
	v_and_b32_e32 v39, 0xffff0000, v26
	v_pk_fma_f32 v[28:29], v[28:29], v[28:29], v[36:37]
	v_and_b32_e32 v37, 0xffff0000, v27
	v_lshlrev_b32_e32 v36, 16, v27
	v_lshlrev_b32_e32 v38, 16, v26
	v_mov_b32_e32 v26, v39
	v_mov_b32_e32 v27, v37
	v_pk_mul_f32 v[26:27], v[26:27], v[26:27]
	v_mov_b32_e32 v40, v38
	v_mov_b32_e32 v41, v36
	s_waitcnt vmcnt(3)
	v_and_b32_e32 v43, 0xffff0000, v31
	v_and_b32_e32 v45, 0xffff0000, v30
	v_pk_fma_f32 v[26:27], v[40:41], v[40:41], v[26:27]
	v_lshlrev_b32_e32 v42, 16, v31
	v_lshlrev_b32_e32 v44, 16, v30
	v_mov_b32_e32 v46, v45
	v_mov_b32_e32 v47, v43
	v_add_f32_e32 v26, v26, v27
	v_mov_b32_e32 v30, v44
	v_mov_b32_e32 v31, v42
	v_pk_mul_f32 v[46:47], v[46:47], v[46:47]
	v_pk_add_f32 v[26:27], v[28:29], v[26:27] op_sel_hi:[1,0]
	v_pk_fma_f32 v[30:31], v[30:31], v[30:31], v[46:47]
	v_mov_b32_e32 v47, v28
	v_mov_b32_e32 v46, v30
	v_mov_b32_e32 v26, v31
	v_pk_add_f32 v[26:27], v[46:47], v[26:27]
	s_nop 1
	v_add_f32_dpp v26, v26, v26 quad_perm:[1,0,3,2] row_mask:0xf bank_mask:0xf
	v_add_f32_dpp v27, v27, v27 quad_perm:[1,0,3,2] row_mask:0xf bank_mask:0xf
	v_lshl_add_u64 v[40:41], s[58:59], 0, v[14:15]
	s_nop 1
	v_add_f32_dpp v26, v26, v26 quad_perm:[2,3,0,1] row_mask:0xf bank_mask:0xf
	v_add_f32_dpp v27, v27, v27 quad_perm:[2,3,0,1] row_mask:0xf bank_mask:0xf
	s_nop 1
	v_add_f32_dpp v26, v26, v26 row_half_mirror row_mask:0xf bank_mask:0xf
	v_add_f32_dpp v27, v27, v27 row_half_mirror row_mask:0xf bank_mask:0xf
	s_nop 1
	v_add_f32_dpp v26, v26, v26 row_mirror row_mask:0xf bank_mask:0xf
	v_add_f32_dpp v27, v27, v27 row_mirror row_mask:0xf bank_mask:0xf
	v_mov_b32_e32 v28, v26
	v_mov_b32_e32 v29, v27
	s_nop 1
	v_permlane16_swap_b32_e32 v28, v26
	v_permlane16_swap_b32_e32 v29, v27
	v_pk_add_f32 v[26:27], v[26:27], v[28:29]
	v_mov_b32_e32 v28, v26
	v_mov_b32_e32 v29, v27
	s_nop 1
	v_permlane32_swap_b32_e32 v28, v26
	v_permlane32_swap_b32_e32 v29, v27
	v_pk_add_f32 v[26:27], v[26:27], v[28:29]
	s_waitcnt lgkmcnt(0)
	s_nop 0
	v_pk_fma_f32 v[30:31], v[26:27], s[52:53], v[18:19] op_sel_hi:[1,1,0]
	s_nop 0
	v_mul_f32_e32 v1, 0x4b800000, v31
	v_cmp_gt_f32_e64 s[38:39], s3, v31
	v_cmp_gt_f32_e32 vcc, s3, v30
	s_nop 0
	v_cndmask_b32_e64 v1, v31, v1, s[38:39]
	v_rsq_f32_e32 v1, v1
	s_nop 0
	v_mul_f32_e32 v25, 0x45800000, v1
	v_cndmask_b32_e64 v46, v1, v25, s[38:39]
	v_mul_f32_e32 v1, 0x4b800000, v30
	v_cndmask_b32_e32 v1, v30, v1, vcc
	v_rsq_f32_e32 v1, v1
	v_pk_mul_f32 v[26:27], v[46:47], v[38:39] op_sel_hi:[0,1]
	v_pk_mul_f32 v[28:29], v[46:47], v[36:37] op_sel_hi:[0,1]
	v_cvt_pk_bf16_f32 v26, v26, v27
	v_cvt_pk_bf16_f32 v27, v28, v29
	v_pk_mul_f32 v[28:29], v[46:47], v[34:35] op_sel_hi:[0,1]
	v_pk_mul_f32 v[32:33], v[46:47], v[32:33] op_sel_hi:[0,1]
	v_cvt_pk_bf16_f32 v28, v28, v29
	v_cvt_pk_bf16_f32 v29, v32, v33
	v_mul_f32_e32 v25, 0x45800000, v1
	global_store_dwordx4 v[40:41], v[26:29], off
	s_nop 1
	v_cndmask_b32_e32 v26, v1, v25, vcc
	v_pk_mul_f32 v[28:29], v[26:27], v[44:45] op_sel_hi:[0,1]
	v_pk_mul_f32 v[26:27], v[26:27], v[42:43] op_sel_hi:[0,1]
	v_cvt_pk_bf16_f32 v28, v28, v29
	v_cvt_pk_bf16_f32 v29, v26, v27
	v_lshl_add_u64 v[26:27], s[58:59], 0, v[10:11]
	global_store_dwordx2 v[26:27], v[28:29], off
	s_and_saveexec_b64 s[38:39], s[0:1]
	s_cbranch_execz .LBB0_299
	v_lshl_add_u64 v[28:29], s[58:59], 0, v[8:9]
	s_waitcnt vmcnt(2)
	v_lshlrev_b32_e32 v1, 16, v104
	v_lshlrev_b32_e32 v25, 16, v105
	v_mov_b32_e32 v26, v106
	v_mov_b32_e32 v27, v107
	v_add_co_u32_e32 v28, vcc, 0x700000, v28
	v_mul_f32_e32 v30, v27, v25
	v_mul_f32_e32 v25, v26, v25
	v_fma_f32 v26, v26, v1, -v30
	v_fmac_f32_e32 v25, v27, v1
	v_bfe_u32 v1, v26, 16, 1
	v_addc_co_u32_e32 v29, vcc, 0, v29, vcc
	v_bfe_u32 v27, v25, 16, 1
	v_add3_u32 v1, v26, v1, s33
	v_add3_u32 v25, v25, v27, s33
	global_store_short_d16_hi v[28:29], v1, off
	global_store_short_d16_hi v[28:29], v25, off offset:64
	s_branch .LBB0_299

; #define PG8_STAGE(bufoff, gbase, voff) do { _Pragma("unroll") for (int _i = 0; _i < 2; ++_i) \
;         __builtin_amdgcn_global_load_lds((const unsigned*)((const char*)(gbase) + (voff)[_i]), (PG8_LAS unsigned*)(lds + (bufoff) + ldsw + _i * 8192), 16, 0, 0); } while (0)
; #define PG8_WAIT_V(n) asm volatile("s_waitcnt vmcnt(" #n ")" ::: "memory")
; #define PG8_BAR __builtin_amdgcn_s_barrier()
; template <class Epi, class Sched, bool ALIGN_EPI = false, bool SP2 = false>
; __device__ __forceinline__ void gemm_phase(PG8_LAS unsigned char* lds, const Gemm g, const Sched& S, const Epi& E) {
;     ...
;         PG8_STAGE(PG8_SB(0, 0), cB, voffB); PG8_STAGE(PG8_SA(0, 0), cA, voffA); PG8_STAGE(PG8_SB(0, 1), cB + hstepB, voffB); PG8_STAGE(PG8_SA(0, 1), cA + hstepA, voffA);
;         if (wr == 1) PG8_BAR;
;         PG8_WAIT_V(4); PG8_BAR;
;         PG8_STAGE(PG8_SB(1, 0), cB + kstep, voffB); PG8_STAGE(PG8_SA(1, 0), cA + kstep, voffA); PG8_STAGE(PG8_SB(1, 1), cB + hstepB + kstep, voffB);
;         PG8_WAIT_V(6); PG8_BAR;
.LBB0_359:
	v_bfe_u32 v16, v12, 4, 2
	v_and_b32_e32 v15, 15, v12
	v_lshlrev_b32_e32 v17, 4, v16
	v_lshlrev_b32_e32 v12, 2, v12
	v_lshl_or_b32 v152, s0, 6, v15
	v_lshl_or_b32 v15, v15, 6, v17
	s_lshl_b32 s0, s0, 13
	v_and_b32_e32 v12, 32, v12
	v_bitop3_b32 v17, v15, s0, v12 bitop3:0xde
	s_lshl_b32 s0, s1, 5
	s_and_b32 s23, s0, 0x60
	s_lshl_b32 s0, s23, 7
	v_bitop3_b32 v153, v15, s0, v12 bitop3:0xde
	s_mov_b64 s[0:1], 0x80
	s_add_i32 m0, s65, 0x18000
	v_lshl_add_u64 v[6:7], v[6:7], 0, s[0:1]
	global_load_lds_dwordx4 v[6:7], off
	v_lshl_add_u64 v[4:5], v[4:5], 0, s[0:1]
	s_add_i32 m0, s65, 0x1a000
	s_add_i32 s93, s65, 0x8000
	s_add_i32 s3, s65, 0xa000
	global_load_lds_dwordx4 v[4:5], off
	v_lshl_add_u64 v[2:3], v[2:3], 0, s[0:1]
	s_mov_b32 m0, s93
	s_add_u32 s36, s44, 0x20080
	global_load_lds_dwordx4 v[2:3], off
	v_lshl_add_u64 v[0:1], v[0:1], 0, s[0:1]
	s_mov_b32 m0, s3
	s_addc_u32 s37, s45, 0
	global_load_lds_dwordx4 v[0:1], off
	s_add_i32 m0, s65, 0x1c000
	v_lshl_add_u64 v[0:1], s[36:37], 0, v[130:131]
	global_load_lds_dwordx4 v[0:1], off
	v_lshl_add_u64 v[0:1], s[36:37], 0, v[134:135]
	s_add_i32 m0, s65, 0x1e000
	s_add_i32 s77, 0, 0x14000
	global_load_lds_dwordx4 v[0:1], off
	s_waitcnt vmcnt(10)
	s_barrier
	v_lshlrev_b32_e32 v0, 6, v16
	v_mov_b32_e32 v1, v131
	v_lshl_add_u64 v[136:137], s[54:55], 0, v[0:1]
	v_lshlrev_b32_e32 v0, 13, v8
	v_and_b32_e32 v0, 0xffffc000, v0
	v_lshl_add_u32 v0, v9, 10, v0
	v_and_b32_e32 v1, 1, v8
	v_lshl_or_b32 v0, v1, 6, v0
	v_lshl_add_u32 v138, v10, 1, v0
	v_lshlrev_b32_e32 v0, 13, v11
	v_and_b32_e32 v0, 0xffffc000, v0
	s_waitcnt vmcnt(6)
	v_lshl_add_u32 v0, v13, 10, v0
	v_and_b32_e32 v1, 1, v11
	v_lshl_or_b32 v0, v1, 6, v0
	s_add_i32 s55, 0, 0x10000
	s_ashr_i32 s33, s92, 31
	s_ashr_i32 s76, s2, 31
	v_lshl_or_b32 v154, v16, 3, s23
	v_mov_b32_e32 v139, v131
	v_lshl_add_u32 v140, v14, 1, v0
	v_mov_b32_e32 v141, v131
	v_mov_b64_e32 v[142:143], 0x180
	v_mov_b64_e32 v[144:145], 0x17f
	v_add_u32_e32 v155, s55, v153
	v_add_u32_e32 v156, 0, v17
	v_add_u32_e32 v157, s77, v153
	s_mov_b32 s54, 0x3dd53b94
	s_movk_i32 s78, 0xc00
	s_barrier
	s_branch .LBB0_361

; #define PG8_STAGE(bufoff, gbase, voff) do { _Pragma("unroll") for (int _i = 0; _i < 2; ++_i) \
;         __builtin_amdgcn_global_load_lds((const unsigned*)((const char*)(gbase) + (voff)[_i]), (PG8_LAS unsigned*)(lds + (bufoff) + ldsw + _i * 8192), 16, 0, 0); } while (0)
; #define PG8_WAIT_V(n) asm volatile("s_waitcnt vmcnt(" #n ")" ::: "memory")
; #define PG8_BAR __builtin_amdgcn_s_barrier()
; template <class Epi, class Sched, bool ALIGN_EPI = false, bool SP2 = false>
; __device__ __forceinline__ void gemm_phase(PG8_LAS unsigned char* lds, const Gemm g, const Sched& S, const Epi& E) {
;     ...
;         PG8_STAGE(PG8_SB(0, 0), cB, voffB); PG8_STAGE(PG8_SA(0, 0), cA, voffA); PG8_STAGE(PG8_SB(0, 1), cB + hstepB, voffB); PG8_STAGE(PG8_SA(0, 1), cA + hstepA, voffA);
;         if (wr == 1) PG8_BAR;
;         PG8_WAIT_V(4); PG8_BAR;
;         PG8_STAGE(PG8_SB(1, 0), cB + kstep, voffB); PG8_STAGE(PG8_SA(1, 0), cA + kstep, voffA); PG8_STAGE(PG8_SB(1, 1), cB + hstepB + kstep, voffB);
;         PG8_WAIT_V(6); PG8_BAR;
.LBB0_392:
	v_lshrrev_b32_e32 v19, 1, v17
	v_and_b32_e32 v19, 24, v19
	v_and_b32_e32 v18, 15, v17
	v_lshlrev_b32_e32 v20, 1, v19
	v_lshlrev_b32_e32 v17, 2, v17
	s_sext_i32_i8 s94, s0
	v_lshl_or_b32 v16, s1, 6, v18
	v_lshl_or_b32 v18, v18, 6, v20
	s_lshl_b32 s0, s1, 13
	v_and_b32_e32 v17, 32, v17
	v_bitop3_b32 v20, v18, s0, v17 bitop3:0xde
	s_lshl_b32 s0, s26, 5
	s_mov_b64 s[26:27], 0x80
	s_and_b32 s22, s0, 0x60
	s_add_i32 m0, s37, 0x18000
	v_lshl_add_u64 v[14:15], v[14:15], 0, s[26:27]
	s_lshl_b32 s0, s22, 7
	global_load_lds_dwordx4 v[14:15], off
	v_lshl_add_u64 v[12:13], v[12:13], 0, s[26:27]
	s_add_i32 m0, s37, 0x1a000
	s_add_i32 s79, s37, 0x8000
	s_add_i32 s80, s37, 0xa000
	v_bitop3_b32 v17, v18, s0, v17 bitop3:0xde
	global_load_lds_dwordx4 v[12:13], off
	v_lshl_add_u64 v[10:11], v[10:11], 0, s[26:27]
	s_mov_b32 m0, s79
	s_add_u32 s0, s96, 0x10080
	global_load_lds_dwordx4 v[10:11], off
	v_lshl_add_u64 v[8:9], v[8:9], 0, s[26:27]
	s_mov_b32 m0, s80
	s_addc_u32 s1, s97, 0
	global_load_lds_dwordx4 v[8:9], off
	s_add_i32 m0, s37, 0x1c000
	v_lshl_add_u64 v[8:9], s[0:1], 0, v[2:3]
	global_load_lds_dwordx4 v[8:9], off
	v_lshl_add_u64 v[8:9], s[0:1], 0, v[6:7]
	s_add_i32 m0, s37, 0x1e000
	s_add_i32 s83, 0, 0x10000
	global_load_lds_dwordx4 v[8:9], off
	s_waitcnt vmcnt(10)
	s_barrier
	s_waitcnt vmcnt(6)
	s_add_i32 s93, 0, 0x14000
	s_ashr_i32 s81, s92, 31
	v_or_b32_e32 v12, s22, v19
	s_add_i32 s82, s2, s92
	s_mov_b64 s[38:39], 0x100
	v_mov_b64_e32 v[8:9], 0x100
	v_mov_b64_e32 v[10:11], 0xff
	v_add_u32_e32 v13, s83, v17
	v_add_u32_e32 v14, 0, v20
	s_add_i32 s84, s37, 0xc000
	s_add_i32 s85, s37, 0xe000
	v_add_u32_e32 v15, s93, v17
	s_mov_b64 s[40:41], 0x180
	s_mov_b64 s[44:45], s[2:3]
	s_barrier
	s_branch .LBB0_395

; #define PG8_STAGE(bufoff, gbase, voff) do { _Pragma("unroll") for (int _i = 0; _i < 2; ++_i) \
;         __builtin_amdgcn_global_load_lds((const unsigned*)((const char*)(gbase) + (voff)[_i]), (PG8_LAS unsigned*)(lds + (bufoff) + ldsw + _i * 8192), 16, 0, 0); } while (0)
; #define PG8_WAIT_V(n) asm volatile("s_waitcnt vmcnt(" #n ")" ::: "memory")
; #define PG8_BAR __builtin_amdgcn_s_barrier()
; template <class Epi, class Sched, bool ALIGN_EPI = false, bool SP2 = false>
; __device__ __forceinline__ void gemm_phase(PG8_LAS unsigned char* lds, const Gemm g, const Sched& S, const Epi& E) {
;     ...
;         PG8_STAGE(PG8_SB(0, 0), cB, voffB); PG8_STAGE(PG8_SA(0, 0), cA, voffA); PG8_STAGE(PG8_SB(0, 1), cB + hstepB, voffB); PG8_STAGE(PG8_SA(0, 1), cA + hstepA, voffA);
;         if (wr == 1) PG8_BAR;
;         PG8_WAIT_V(4); PG8_BAR;
;         PG8_STAGE(PG8_SB(1, 0), cB + kstep, voffB); PG8_STAGE(PG8_SA(1, 0), cA + kstep, voffA); PG8_STAGE(PG8_SB(1, 1), cB + hstepB + kstep, voffB);
;         PG8_WAIT_V(6); PG8_BAR;
.LBB0_410:
	v_lshrrev_b32_e32 v19, 1, v17
	v_and_b32_e32 v19, 24, v19
	v_and_b32_e32 v18, 15, v17
	v_lshlrev_b32_e32 v20, 1, v19
	v_lshlrev_b32_e32 v17, 2, v17
	s_sext_i32_i16 s85, s0
	v_lshl_or_b32 v16, s1, 6, v18
	v_lshl_or_b32 v18, v18, 6, v20
	s_lshl_b32 s0, s1, 13
	v_and_b32_e32 v17, 32, v17
	v_bitop3_b32 v20, v18, s0, v17 bitop3:0xde
	s_lshl_b32 s0, s22, 5
	s_mov_b64 s[22:23], 0x80
	s_and_b32 s36, s0, 0x60
	s_add_i32 m0, s27, 0x18000
	v_lshl_add_u64 v[14:15], v[14:15], 0, s[22:23]
	s_lshl_b32 s0, s36, 7
	global_load_lds_dwordx4 v[14:15], off
	v_lshl_add_u64 v[12:13], v[12:13], 0, s[22:23]
	s_add_i32 m0, s27, 0x1a000
	s_add_i32 s77, s27, 0x8000
	s_add_i32 s78, s27, 0xa000
	v_bitop3_b32 v17, v18, s0, v17 bitop3:0xde
	global_load_lds_dwordx4 v[12:13], off
	v_lshl_add_u64 v[10:11], v[10:11], 0, s[22:23]
	s_mov_b32 m0, s77
	s_add_u32 s0, s64, 0x10080
	global_load_lds_dwordx4 v[10:11], off
	v_lshl_add_u64 v[8:9], v[8:9], 0, s[22:23]
	s_mov_b32 m0, s78
	s_addc_u32 s1, s65, 0
	global_load_lds_dwordx4 v[8:9], off
	s_add_i32 m0, s27, 0x1c000
	v_lshl_add_u64 v[8:9], s[0:1], 0, v[2:3]
	global_load_lds_dwordx4 v[8:9], off
	v_lshl_add_u64 v[8:9], s[0:1], 0, v[6:7]
	s_add_i32 m0, s27, 0x1e000
	s_add_i32 s81, 0, 0x10000
	global_load_lds_dwordx4 v[8:9], off
	s_waitcnt vmcnt(10)
	s_barrier
	s_waitcnt vmcnt(6)
	s_add_i32 s84, 0, 0x14000
	s_ashr_i32 s79, s92, 31
	v_or_b32_e32 v12, s36, v19
	s_add_i32 s80, s2, s92
	s_mov_b64 s[36:37], 0x100
	v_mov_b64_e32 v[8:9], 0x100
	v_mov_b64_e32 v[10:11], 0xff
	v_add_u32_e32 v13, s81, v17
	v_add_u32_e32 v14, 0, v20
	s_add_i32 s82, s27, 0xc000
	s_add_i32 s83, s27, 0xe000
	v_add_u32_e32 v15, s84, v17
	s_mov_b64 s[38:39], 0x180
	s_mov_b64 s[40:41], s[2:3]
	s_barrier
	s_branch .LBB0_413

; #define PG8_STAGE(bufoff, gbase, voff) do { _Pragma("unroll") for (int _i = 0; _i < 2; ++_i) \
;         __builtin_amdgcn_global_load_lds((const unsigned*)((const char*)(gbase) + (voff)[_i]), (PG8_LAS unsigned*)(lds + (bufoff) + ldsw + _i * 8192), 16, 0, 0); } while (0)
; #define PG8_WAIT_V(n) asm volatile("s_waitcnt vmcnt(" #n ")" ::: "memory")
; #define PG8_BAR __builtin_amdgcn_s_barrier()
; template <class Epi, class Sched, bool ALIGN_EPI = false, bool SP2 = false>
; __device__ __forceinline__ void gemm_phase(PG8_LAS unsigned char* lds, const Gemm g, const Sched& S, const Epi& E) {
;     ...
;         PG8_STAGE(PG8_SB(0, 0), cB, voffB); PG8_STAGE(PG8_SB(0, 1), cB + hstepB, voffB); PG8_STAGE(PG8_SA(0, 0), cA, voffA); PG8_STAGE(PG8_SA(0, 1), cA + hstepA, voffA);
;         if (wr == 1) PG8_BAR;
;         PG8_WAIT_V(2); PG8_BAR;
;         PG8_STAGE(PG8_SB(1, 0), cB + kstep, voffB); PG8_STAGE(PG8_SA(1, 0), cA + kstep, voffA); PG8_STAGE(PG8_SB(1, 1), cB + hstepB + kstep, voffB);
;         PG8_WAIT_V(6); PG8_BAR;
.LBB0_722:
	v_lshrrev_b32_e32 v16, 1, v14
	v_and_b32_e32 v16, 24, v16
	v_and_b32_e32 v15, 15, v14
	v_lshlrev_b32_e32 v17, 1, v16
	v_lshlrev_b32_e32 v14, 2, v14
	s_sext_i32_i8 s27, s22
	v_lshl_or_b32 v144, s31, 6, v15
	v_lshl_or_b32 v15, v15, 6, v17
	s_lshl_b32 s22, s31, 13
	v_and_b32_e32 v14, 32, v14
	v_bitop3_b32 v17, v15, s22, v14 bitop3:0xde
	s_lshl_b32 s22, s30, 5
	s_mov_b64 s[30:31], 0x80
	s_and_b32 s36, s22, 0x60
	s_add_i32 m0, s43, 0x18000
	v_lshl_add_u64 v[6:7], v[6:7], 0, s[30:31]
	s_lshl_b32 s22, s36, 7
	global_load_lds_dwordx4 v[6:7], off
	v_lshl_add_u64 v[2:3], v[2:3], 0, s[30:31]
	s_add_i32 m0, s43, 0x1a000
	s_add_i32 s66, s43, 0x8000
	s_add_i32 s67, s43, 0xa000
	global_load_lds_dwordx4 v[2:3], off
	v_lshl_add_u64 v[0:1], v[0:1], 0, s[30:31]
	s_mov_b32 m0, s66
	s_add_u32 s34, s52, 0x80080
	global_load_lds_dwordx4 v[0:1], off
	v_lshl_add_u64 v[0:1], v[4:5], 0, s[30:31]
	s_mov_b32 m0, s67
	s_addc_u32 s35, s53, 0
	global_load_lds_dwordx4 v[0:1], off
	s_add_i32 m0, s43, 0x1c000
	v_lshl_add_u64 v[0:1], s[34:35], 0, v[130:131]
	global_load_lds_dwordx4 v[0:1], off
	v_lshl_add_u64 v[0:1], s[34:35], 0, v[134:135]
	s_add_i32 m0, s43, 0x1e000
	s_cmpk_lt_u32 s23, 0x100
	global_load_lds_dwordx4 v[0:1], off
	s_waitcnt vmcnt(8)
	s_barrier
	v_lshlrev_b32_e32 v0, 15, v8
	v_and_b32_e32 v0, 0xffff0000, v0
	v_lshl_add_u32 v0, v9, 12, v0
	v_and_b32_e32 v1, 1, v8
	v_lshl_or_b32 v0, v1, 6, v0
	v_lshl_add_u32 v136, v10, 1, v0
	v_lshlrev_b32_e32 v0, 15, v11
	v_and_b32_e32 v0, 0xffff0000, v0
	s_waitcnt vmcnt(6)
	v_lshl_add_u32 v0, v12, 12, v0
	v_and_b32_e32 v1, 1, v11
	v_bitop3_b32 v145, v15, s22, v14 bitop3:0xde
	s_cselect_b64 s[22:23], -1, 0
	v_lshl_or_b32 v0, v1, 6, v0
	s_add_i32 s69, 0, 0x10000
	s_add_i32 s70, 0, 0x14000
	s_ashr_i32 s68, s92, 31
	v_or_b32_e32 v146, s36, v16
	v_mov_b32_e32 v137, v131
	v_lshl_add_u32 v138, v13, 1, v0
	v_mov_b32_e32 v139, v131
	v_mov_b64_e32 v[140:141], 0x200
	v_mov_b64_e32 v[142:143], 0x1ff
	v_add_u32_e32 v147, s69, v145
	v_add_u32_e32 v148, s70, v145
	v_add_u32_e32 v149, 0, v17
	s_barrier
	s_branch .LBB0_725

; __device__ __forceinline__ void p7_rows(const Params& P, LAS unsigned char* lds, int G) {
;     ...
;     for (int m = blockIdx.x * 8 + wave; m < M; m += G * 8) {
;         const int b = m >> 13; const f32x4* xr = (const f32x4*)(P.x + (size_t)m * DM) + lane; const u32x2* orow = (const u32x2*)(O + (size_t)m * DM) + lane;
;         f32x4 v[8], xv[8]; float ss = 0.f;
; #pragma unroll
;         for (int j = 0; j < 8; ++j) xv[j] = __builtin_nontemporal_load(xr + 64 * j);
; #pragma unroll
;         for (int j = 0; j < 8; ++j) { const u32x2 w = __builtin_nontemporal_load(orow + 64 * j); v[j][0] = __uint_as_float(w.x << 16); v[j][1] = __uint_as_float(w.x & 0xffff0000u); v[j][2] = __uint_as_float(w.y << 16); v[j][3] = __uint_as_float(w.y & 0xffff0000u);
;             ss += (v[j][0] * v[j][0] + v[j][1] * v[j][1]) + (v[j][2] * v[j][2] + v[j][3] * v[j][3]); }
;         const float rstd = rsqrtf(wave_sum(ss) * (1.0f / DM) + RMS_EPS);
.LBB0_803:
	v_add_co_u32_e32 v38, vcc, 0xf0800000, v36
	s_mov_b32 s33, 0xf0801000
	s_nop 0
	v_addc_co_u32_e32 v39, vcc, -1, v37, vcc
	v_add_co_u32_e32 v40, vcc, s33, v36
	global_load_dwordx4 v[28:31], v[34:35], off offset:-4096 nt
	global_load_dwordx4 v[24:27], v[34:35], off offset:-3072 nt
	global_load_dwordx4 v[20:23], v[34:35], off offset:-2048 nt
	global_load_dwordx4 v[16:19], v[34:35], off offset:-1024 nt
	global_load_dwordx4 v[12:15], v[34:35], off nt
	global_load_dwordx4 v[8:11], v[34:35], off offset:1024 nt
	global_load_dwordx4 v[4:7], v[34:35], off offset:2048 nt
	global_load_dwordx4 v[0:3], v[34:35], off offset:3072 nt
	v_addc_co_u32_e32 v41, vcc, -1, v37, vcc
	global_load_dwordx2 v[38:39], v[38:39], off nt
	s_mov_b32 s33, 0xec800000
	global_load_dwordx2 v[42:43], v[40:41], off offset:-3584 nt
	global_load_dwordx2 v[44:45], v[40:41], off offset:-3072 nt
	global_load_dwordx2 v[90:91], v[40:41], off offset:-2560 nt
	global_load_dwordx2 v[92:93], v[40:41], off offset:-2048 nt
	global_load_dwordx2 v[94:95], v[40:41], off offset:-1536 nt
	global_load_dwordx2 v[96:97], v[40:41], off offset:-1024 nt
	global_load_dwordx2 v[98:99], v[40:41], off offset:-512 nt
	v_lshl_add_u64 v[34:35], v[34:35], 0, s[22:23]
	s_waitcnt vmcnt(7)
	v_and_b32_e32 v67, 0xffff0000, v38
	v_and_b32_e32 v69, 0xffff0000, v39
	v_lshlrev_b32_e32 v66, 16, v38
	s_waitcnt vmcnt(5)
	v_lshlrev_b32_e32 v58, 16, v44
	v_and_b32_e32 v59, 0xffff0000, v44
	v_lshlrev_b32_e32 v60, 16, v45
	v_and_b32_e32 v61, 0xffff0000, v45
	v_lshlrev_b32_e32 v68, 16, v39
	v_mul_f32_e32 v38, v69, v69
	v_and_b32_e32 v73, 0xffff0000, v43
	v_and_b32_e32 v72, 0xffff0000, v42
	v_pk_fma_f32 v[38:39], v[68:69], v[68:69], v[38:39] op_sel_hi:[1,1,0]
	v_lshlrev_b32_e32 v71, 16, v43
	v_lshlrev_b32_e32 v70, 16, v42
	v_pk_mul_f32 v[42:43], v[72:73], v[72:73]
	v_mov_b32_e32 v46, v38
	v_pk_fma_f32 v[42:43], v[70:71], v[70:71], v[42:43]
	s_waitcnt vmcnt(4)
	v_mov_b32_e32 v44, v90
	v_mov_b32_e32 v45, v91
	v_lshlrev_b32_e32 v55, 16, v44
	v_and_b32_e32 v51, 0xffff0000, v44
	v_mul_f32_e32 v44, v67, v67
	v_lshlrev_b32_e32 v48, 16, v45
	v_and_b32_e32 v49, 0xffff0000, v45
	v_pk_fma_f32 v[44:45], v[66:67], v[66:67], v[44:45] op_sel_hi:[1,1,0]
	v_mov_b32_e32 v47, v55
	v_mov_b32_e32 v54, v44
	v_mul_f32_e32 v50, v51, v51
	v_pk_add_f32 v[38:39], v[44:45], v[38:39]
	v_pk_mul_f32 v[44:45], v[54:55], v[46:47]
	v_pk_add_f32 v[42:43], v[42:43], v[42:43] op_sel:[0,1] op_sel_hi:[1,0]
	v_mov_b32_e32 v39, v45
	v_mov_b32_e32 v43, v50
	v_pk_add_f32 v[38:39], v[38:39], v[42:43]
	v_mul_f32_e32 v42, v59, v59
	v_mul_f32_e32 v44, v61, v61
	v_mul_f32_e32 v52, v48, v48
	v_mul_f32_e32 v53, v49, v49
	v_pk_fma_f32 v[42:43], v[58:59], v[58:59], v[42:43] op_sel_hi:[1,1,0]
	v_pk_fma_f32 v[44:45], v[60:61], v[60:61], v[44:45] op_sel_hi:[1,1,0]
	v_mov_b32_e32 v43, v52
	v_mov_b32_e32 v45, v53
	v_pk_add_f32 v[42:43], v[42:43], v[44:45]
	s_nop 0
	v_pk_add_f32 v[82:83], v[38:39], v[42:43]
	v_pk_add_f32 v[82:83], v[82:83], v[82:83] op_sel:[0,1] op_sel_hi:[1,0]
	s_waitcnt vmcnt(3)
	v_mov_b32_e32 v38, v92
	v_mov_b32_e32 v39, v93
	v_and_b32_e32 v65, 0xffff0000, v39
	v_and_b32_e32 v64, 0xffff0000, v38
	v_lshlrev_b32_e32 v63, 16, v39
	v_lshlrev_b32_e32 v62, 16, v38
	v_pk_mul_f32 v[38:39], v[64:65], v[64:65]
	v_mov_b32_e32 v42, v82
	v_pk_fma_f32 v[38:39], v[62:63], v[62:63], v[38:39]
	s_nop 0
	v_pk_add_f32 v[84:85], v[38:39], v[38:39] op_sel:[0,1] op_sel_hi:[1,0]
	v_mov_b32_e32 v88, v84
	v_pk_add_f32 v[82:83], v[82:83], v[84:85]
	s_waitcnt vmcnt(2)
	v_mov_b32_e32 v38, v94
	v_mov_b32_e32 v39, v95
	v_and_b32_e32 v57, 0xffff0000, v39
	v_and_b32_e32 v56, 0xffff0000, v38
	v_lshlrev_b32_e32 v53, 16, v39
	v_lshlrev_b32_e32 v52, 16, v38
	v_pk_mul_f32 v[38:39], v[56:57], v[56:57]
	s_nop 0
	v_pk_fma_f32 v[86:87], v[52:53], v[52:53], v[38:39]
	s_waitcnt vmcnt(1)
	v_mov_b32_e32 v38, v96
	v_mov_b32_e32 v39, v97
	v_lshlrev_b32_e32 v44, 16, v38
	v_and_b32_e32 v45, 0xffff0000, v38
	v_lshlrev_b32_e32 v46, 16, v39
	v_and_b32_e32 v47, 0xffff0000, v39
	s_waitcnt vmcnt(0)
	v_mov_b32_e32 v38, v98
	v_mov_b32_e32 v39, v99
	v_lshlrev_b32_e32 v43, 16, v38
	v_mov_b32_e32 v89, v43
	v_and_b32_e32 v41, 0xffff0000, v38
	v_pk_mul_f32 v[84:85], v[42:43], v[88:89]
	v_mul_f32_e32 v40, v41, v41
	v_mov_b32_e32 v83, v85
	v_pk_add_f32 v[84:85], v[86:87], v[86:87] op_sel:[0,1] op_sel_hi:[1,0]
	v_lshlrev_b32_e32 v38, 16, v39
	v_mov_b32_e32 v85, v40
	v_mul_f32_e32 v40, v45, v45
	v_and_b32_e32 v39, 0xffff0000, v39
	v_pk_add_f32 v[82:83], v[82:83], v[84:85]
	v_pk_fma_f32 v[84:85], v[44:45], v[44:45], v[40:41] op_sel_hi:[1,1,0]
	v_mul_f32_e32 v40, v47, v47
	v_mul_f32_e32 v50, v38, v38
	v_mul_f32_e32 v54, v39, v39
	v_pk_fma_f32 v[86:87], v[46:47], v[46:47], v[40:41] op_sel_hi:[1,1,0]
	v_mov_b32_e32 v85, v50
	v_mov_b32_e32 v87, v54
	v_pk_add_f32 v[84:85], v[84:85], v[86:87]
	v_mov_b32_e32 v50, v55
	v_pk_add_f32 v[82:83], v[82:83], v[84:85]
	s_nop 0
	v_add_f32_e32 v40, v82, v83
	s_nop 1
	v_add_f32_dpp v40, v40, v40 quad_perm:[1,0,3,2] row_mask:0xf bank_mask:0xf
	s_nop 1
	v_add_f32_dpp v40, v40, v40 quad_perm:[2,3,0,1] row_mask:0xf bank_mask:0xf
	s_nop 1
	v_add_f32_dpp v40, v40, v40 row_half_mirror row_mask:0xf bank_mask:0xf
	s_nop 1
	v_add_f32_dpp v40, v40, v40 row_mirror row_mask:0xf bank_mask:0xf
	v_mov_b32_e32 v42, v40
	s_nop 1
	v_permlane16_swap_b32_e32 v42, v40
	v_add_f32_e32 v40, v40, v42
	v_mov_b32_e32 v42, v40
	s_nop 1
	v_permlane32_swap_b32_e32 v42, v40
	v_add_f32_e32 v40, v40, v42
	s_waitcnt lgkmcnt(0)
; #define LAS __attribute__((address_space(3)))
; __device__ __forceinline__ unsigned pk2(float lo, float hi) { return pg8::cvtpk(lo, hi); }
; __device__ __forceinline__ void p7_rows(const Params& P, LAS unsigned char* lds, int G) {
;     ...
;         const float rstd = rsqrtf(wave_sum(ss) * (1.0f / DM) + RMS_EPS);
;         float s2 = 0.f; u32x2* x1r = (u32x2*)((bf16_t*)(P.ws + WS_X1) + (size_t)m * DM) + lane;
; #pragma unroll
;         for (int j = 0; j < 8; ++j) { const f32x4 a = *(const LAS f32x4*)(TA + b * DM + 256 * j + 4 * lane); const f32x4 x1 = xv[j] + v[j] * rstd * a; v[j] = x1; { u32x2 w; w.x = pk2(x1[0], x1[1]); w.y = pk2(x1[2], x1[3]); __builtin_nontemporal_store(w, x1r + 64 * j); }
;             s2 += (x1[0] * x1[0] + x1[1] * x1[1]) + (x1[2] * x1[2] + x1[3] * x1[3]); }
	v_fmamk_f32 v40, v40, 0x3a000000, v33
	v_cmp_gt_f32_e32 vcc, s3, v40
	v_mul_f32_e32 v42, 0x4b800000, v40
	s_nop 0
	v_cndmask_b32_e32 v40, v40, v42, vcc
	v_rsq_f32_e32 v40, v40
	s_nop 0
	v_mul_f32_e32 v42, 0x45800000, v40
	v_cndmask_b32_e32 v42, v40, v42, vcc
	v_and_b32_e32 v40, 0xffffe000, v32
	v_add_u32_e32 v54, v80, v40
	ds_read_b128 v[82:85], v54
	v_pk_mul_f32 v[66:67], v[42:43], v[66:67] op_sel_hi:[0,1]
	v_pk_mul_f32 v[68:69], v[42:43], v[68:69] op_sel_hi:[0,1]
	v_pk_mul_f32 v[50:51], v[50:51], v[42:43] op_sel_hi:[1,0]
	v_pk_mul_f32 v[48:49], v[48:49], v[42:43] op_sel_hi:[1,0]
	s_waitcnt lgkmcnt(0)
	v_pk_fma_f32 v[84:85], v[84:85], v[68:69], v[30:31]
	v_pk_fma_f32 v[82:83], v[82:83], v[66:67], v[28:29]
	v_cvt_pk_bf16_f32 v29, v84, v85
	v_cvt_pk_bf16_f32 v28, v82, v83
	global_store_dwordx2 v[36:37], v[28:29], off nt
	ds_read_b128 v[28:31], v54 offset:1024
	v_mov_b32_e32 v66, v70
	v_mov_b32_e32 v67, v72
	v_mov_b32_e32 v72, v71
	v_pk_mul_f32 v[66:67], v[42:43], v[66:67] op_sel_hi:[0,1]
	v_pk_mul_f32 v[68:69], v[42:43], v[72:73] op_sel_hi:[0,1]
	s_waitcnt lgkmcnt(0)
	v_pk_fma_f32 v[26:27], v[30:31], v[68:69], v[26:27]
	v_pk_fma_f32 v[28:29], v[28:29], v[66:67], v[24:25]
	v_cvt_pk_bf16_f32 v25, v26, v27
	v_cvt_pk_bf16_f32 v24, v28, v29
	v_mov_b32_e32 v30, v83
	v_mov_b32_e32 v31, v29
	global_store_dwordx2 v[36:37], v[24:25], off offset:512 nt
	v_mov_b32_e32 v24, v82
	v_mov_b32_e32 v25, v28
	v_pk_mul_f32 v[30:31], v[30:31], v[30:31]
	v_mov_b32_e32 v66, v85
	v_mov_b32_e32 v67, v27
	v_pk_fma_f32 v[24:25], v[24:25], v[24:25], v[30:31]
	v_mov_b32_e32 v30, v84
	v_mov_b32_e32 v31, v26
	v_pk_mul_f32 v[66:67], v[66:67], v[66:67]
	v_pk_mul_f32 v[44:45], v[42:43], v[44:45] op_sel_hi:[0,1]
	v_pk_fma_f32 v[30:31], v[30:31], v[30:31], v[66:67]
	ds_read_b128 v[66:69], v54 offset:2048
	v_pk_add_f32 v[24:25], v[24:25], v[30:31]
	v_pk_mul_f32 v[30:31], v[42:43], v[58:59] op_sel_hi:[0,1]
	v_pk_mul_f32 v[58:59], v[42:43], v[60:61] op_sel_hi:[0,1]
	v_pk_add_f32 v[24:25], v[24:25], v[24:25] op_sel_hi:[0,1]
	s_waitcnt lgkmcnt(0)
	v_pk_fma_f32 v[22:23], v[68:69], v[58:59], v[22:23]
	v_pk_fma_f32 v[20:21], v[66:67], v[30:31], v[20:21]
	v_cvt_pk_bf16_f32 v31, v22, v23
	v_cvt_pk_bf16_f32 v30, v20, v21
	global_store_dwordx2 v[36:37], v[30:31], off offset:1024 nt
	v_pk_mul_f32 v[30:31], v[22:23], v[22:23]
	v_pk_mul_f32 v[58:59], v[20:21], v[20:21]
	v_mov_b32_e32 v66, v62
	v_pk_mov_b32 v[60:61], v[58:59], v[30:31] op_sel:[1,0]
	v_mov_b32_e32 v59, v31
	v_pk_add_f32 v[30:31], v[60:61], v[58:59]
	ds_read_b128 v[58:61], v54 offset:3072
	v_mov_b32_e32 v67, v64
	v_mov_b32_e32 v64, v63
	v_pk_mul_f32 v[66:67], v[42:43], v[66:67] op_sel_hi:[0,1]
	v_pk_mul_f32 v[62:63], v[42:43], v[64:65] op_sel_hi:[0,1]
	s_waitcnt lgkmcnt(0)
	v_pk_fma_f32 v[18:19], v[60:61], v[48:49], v[18:19]
	v_pk_fma_f32 v[16:17], v[58:59], v[50:51], v[16:17]
	v_cvt_pk_bf16_f32 v49, v18, v19
	v_cvt_pk_bf16_f32 v48, v16, v17
	global_store_dwordx2 v[36:37], v[48:49], off offset:1536 nt
	ds_read_b128 v[48:51], v54 offset:4096
	v_mul_f32_e32 v24, v16, v16
	v_pk_fma_f32 v[58:59], v[16:17], v[16:17], v[24:25] op_sel_hi:[1,1,0]
	v_mul_f32_e32 v24, v18, v18
	v_pk_add_f32 v[30:31], v[30:31], v[30:31] op_sel_hi:[0,1]
	v_pk_fma_f32 v[60:61], v[18:19], v[18:19], v[24:25] op_sel_hi:[1,1,0]
	s_waitcnt lgkmcnt(0)
	v_pk_fma_f32 v[14:15], v[50:51], v[62:63], v[14:15]
	v_pk_fma_f32 v[12:13], v[48:49], v[66:67], v[12:13]
	v_cvt_pk_bf16_f32 v49, v14, v15
	v_cvt_pk_bf16_f32 v48, v12, v13
	v_mul_f32_e32 v58, v12, v12
	v_mul_f32_e32 v60, v13, v13
	v_mul_f32_e32 v30, v14, v14
	v_mul_f32_e32 v24, v15, v15
	global_store_dwordx2 v[36:37], v[48:49], off offset:2048 nt
	v_pk_add_f32 v[48:49], v[58:59], v[60:61]
	v_pk_add_f32 v[24:25], v[30:31], v[24:25]
	v_mov_b32_e32 v30, v52
	v_pk_add_f32 v[24:25], v[48:49], v[24:25]
	ds_read_b128 v[48:51], v54 offset:5120
	v_mov_b32_e32 v31, v56
	v_mov_b32_e32 v56, v53
	v_pk_mul_f32 v[30:31], v[42:43], v[30:31] op_sel_hi:[0,1]
	v_pk_mul_f32 v[52:53], v[42:43], v[56:57] op_sel_hi:[0,1]
	s_waitcnt lgkmcnt(0)
	v_pk_fma_f32 v[10:11], v[50:51], v[52:53], v[10:11]
	v_pk_fma_f32 v[8:9], v[48:49], v[30:31], v[8:9]
	v_cvt_pk_bf16_f32 v31, v10, v11
	v_cvt_pk_bf16_f32 v30, v8, v9
	global_store_dwordx2 v[36:37], v[30:31], off offset:2560 nt
	v_pk_mul_f32 v[30:31], v[10:11], v[10:11]
	v_pk_mul_f32 v[48:49], v[8:9], v[8:9]
	v_pk_mul_f32 v[46:47], v[42:43], v[46:47] op_sel_hi:[0,1]
	v_pk_mov_b32 v[50:51], v[48:49], v[30:31] op_sel:[1,0]
	v_mov_b32_e32 v49, v31
	v_pk_add_f32 v[30:31], v[50:51], v[48:49]
	ds_read_b128 v[48:51], v54 offset:6144
	v_pk_add_f32 v[24:25], v[24:25], v[24:25] op_sel_hi:[0,1]
	v_mov_b32_e32 v40, v43
	v_pk_mul_f32 v[40:41], v[40:41], v[42:43] op_sel_hi:[1,0]
	v_pk_mul_f32 v[38:39], v[38:39], v[42:43] op_sel_hi:[1,0]
	s_waitcnt lgkmcnt(0)
	v_pk_fma_f32 v[6:7], v[50:51], v[46:47], v[6:7]
	v_pk_fma_f32 v[4:5], v[48:49], v[44:45], v[4:5]
	v_cvt_pk_bf16_f32 v45, v6, v7
	v_cvt_pk_bf16_f32 v44, v4, v5
	global_store_dwordx2 v[36:37], v[44:45], off offset:3072 nt
	ds_read_b128 v[44:47], v54 offset:7168
	v_mul_f32_e32 v24, v4, v4
	v_pk_fma_f32 v[48:49], v[4:5], v[4:5], v[24:25] op_sel_hi:[1,1,0]
	v_mul_f32_e32 v24, v6, v6
	v_pk_add_f32 v[30:31], v[30:31], v[30:31] op_sel_hi:[0,1]
	v_pk_fma_f32 v[50:51], v[6:7], v[6:7], v[24:25] op_sel_hi:[1,1,0]
	s_waitcnt lgkmcnt(0)
; #define LAS __attribute__((address_space(3)))
; __device__ __forceinline__ unsigned pk2(float lo, float hi) { return pg8::cvtpk(lo, hi); }
; __device__ __forceinline__ void p7_rows(const Params& P, LAS unsigned char* lds, int G) {
;     ...
;             s2 += (x1[0] * x1[0] + x1[1] * x1[1]) + (x1[2] * x1[2] + x1[3] * x1[3]); }
;         const float rstd2 = rsqrtf(wave_sum(s2) * (1.0f / DM) + RMS_EPS);
;         u32x2* o = (u32x2*)(XN + (size_t)m * DM) + lane;
; #pragma unroll
;         for (int j = 0; j < 8; ++j) { const f32x4 a = *(const LAS f32x4*)(TB + b * DM + 256 * j + 4 * lane), c = *(const LAS f32x4*)(TC + b * DM + 256 * j + 4 * lane);
;             const f32x4 h = v[j] * rstd2 * a + c; u32x2 w; w.x = pk2(h[0], h[1]); w.y = pk2(h[2], h[3]); o[64 * j] = w; }
	v_pk_fma_f32 v[2:3], v[46:47], v[38:39], v[2:3]
	v_pk_fma_f32 v[0:1], v[44:45], v[40:41], v[0:1]
	v_cvt_pk_bf16_f32 v39, v2, v3
	v_cvt_pk_bf16_f32 v38, v0, v1
	v_mul_f32_e32 v48, v0, v0
	v_mul_f32_e32 v50, v1, v1
	v_mul_f32_e32 v30, v2, v2
	v_mul_f32_e32 v24, v3, v3
	global_store_dwordx2 v[36:37], v[38:39], off offset:3584 nt
	v_pk_add_f32 v[38:39], v[48:49], v[50:51]
	v_pk_add_f32 v[24:25], v[30:31], v[24:25]
	v_add_u32_e32 v32, s42, v32
	v_pk_add_f32 v[24:25], v[38:39], v[24:25]
	ds_read_b128 v[38:41], v54 offset:16384
	ds_read_b128 v[42:45], v54 offset:32768
	v_add_f32_e32 v24, v24, v25
	s_nop 1
	v_add_f32_dpp v24, v24, v24 quad_perm:[1,0,3,2] row_mask:0xf bank_mask:0xf
	s_nop 1
	v_add_f32_dpp v24, v24, v24 quad_perm:[2,3,0,1] row_mask:0xf bank_mask:0xf
	s_nop 1
	v_add_f32_dpp v24, v24, v24 row_half_mirror row_mask:0xf bank_mask:0xf
	s_nop 1
	v_add_f32_dpp v24, v24, v24 row_mirror row_mask:0xf bank_mask:0xf
	v_mov_b32_e32 v25, v24
	s_nop 1
	v_permlane16_swap_b32_e32 v25, v24
	v_add_f32_e32 v24, v24, v25
	v_mov_b32_e32 v25, v24
	s_nop 1
	v_permlane32_swap_b32_e32 v25, v24
	v_add_f32_e32 v24, v24, v25
	s_waitcnt lgkmcnt(0)
	v_fmamk_f32 v24, v24, 0x3a000000, v33
	v_cmp_gt_f32_e32 vcc, s3, v24
	v_mul_f32_e32 v25, 0x4b800000, v24
	s_nop 0
	v_cndmask_b32_e32 v24, v24, v25, vcc
	v_rsq_f32_e32 v24, v24
	s_nop 0
	v_mul_f32_e32 v25, 0x45800000, v24
	v_cndmask_b32_e32 v24, v24, v25, vcc
	v_pk_mul_f32 v[30:31], v[82:83], v[24:25] op_sel_hi:[1,0]
	v_pk_mul_f32 v[46:47], v[84:85], v[24:25] op_sel_hi:[1,0]
	v_pk_fma_f32 v[30:31], v[38:39], v[30:31], v[42:43]
	v_pk_fma_f32 v[40:41], v[40:41], v[46:47], v[44:45]
	v_add_co_u32_e32 v38, vcc, s33, v36
	v_cvt_pk_bf16_f32 v30, v30, v31
	v_cvt_pk_bf16_f32 v31, v40, v41
	v_addc_co_u32_e32 v39, vcc, -1, v37, vcc
	global_store_dwordx2 v[38:39], v[30:31], off
	ds_read_b128 v[38:41], v54 offset:17408
	ds_read_b128 v[42:45], v54 offset:33792
	v_pk_mul_f32 v[28:29], v[28:29], v[24:25] op_sel_hi:[1,0]
	v_pk_mul_f32 v[26:27], v[26:27], v[24:25] op_sel_hi:[1,0]
	s_mov_b32 s33, 0xec801000
	v_pk_mul_f32 v[20:21], v[20:21], v[24:25] op_sel_hi:[1,0]
	s_waitcnt lgkmcnt(0)
	v_pk_fma_f32 v[30:31], v[40:41], v[26:27], v[44:45]
	v_pk_fma_f32 v[26:27], v[38:39], v[28:29], v[42:43]
	v_pk_mul_f32 v[22:23], v[22:23], v[24:25] op_sel_hi:[1,0]
	v_cvt_pk_bf16_f32 v26, v26, v27
	v_cvt_pk_bf16_f32 v27, v30, v31
	v_add_co_u32_e32 v30, vcc, s33, v36
	v_pk_mul_f32 v[16:17], v[16:17], v[24:25] op_sel_hi:[1,0]
	s_nop 0
	v_addc_co_u32_e32 v31, vcc, -1, v37, vcc
	global_store_dwordx2 v[30:31], v[26:27], off offset:-3584
	ds_read_b128 v[26:29], v54 offset:18432
	ds_read_b128 v[38:41], v54 offset:34816
	v_pk_mul_f32 v[18:19], v[18:19], v[24:25] op_sel_hi:[1,0]
	v_pk_mul_f32 v[12:13], v[12:13], v[24:25] op_sel_hi:[1,0]
	v_pk_mul_f32 v[14:15], v[14:15], v[24:25] op_sel_hi:[1,0]
	v_pk_mul_f32 v[8:9], v[8:9], v[24:25] op_sel_hi:[1,0]
	s_waitcnt lgkmcnt(0)
	v_pk_fma_f32 v[22:23], v[28:29], v[22:23], v[40:41]
	v_pk_fma_f32 v[20:21], v[26:27], v[20:21], v[38:39]
	v_pk_mul_f32 v[10:11], v[10:11], v[24:25] op_sel_hi:[1,0]
	v_cvt_pk_bf16_f32 v20, v20, v21
	v_cvt_pk_bf16_f32 v21, v22, v23
	global_store_dwordx2 v[30:31], v[20:21], off offset:-3072
	ds_read_b128 v[20:23], v54 offset:19456
	ds_read_b128 v[26:29], v54 offset:35840
	v_pk_mul_f32 v[4:5], v[4:5], v[24:25] op_sel_hi:[1,0]
	v_pk_mul_f32 v[6:7], v[6:7], v[24:25] op_sel_hi:[1,0]
	v_pk_mul_f32 v[0:1], v[0:1], v[24:25] op_sel_hi:[1,0]
	v_pk_mul_f32 v[2:3], v[2:3], v[24:25] op_sel_hi:[1,0]
	s_waitcnt lgkmcnt(0)
	v_pk_fma_f32 v[18:19], v[22:23], v[18:19], v[28:29]
	v_pk_fma_f32 v[16:17], v[20:21], v[16:17], v[26:27]
	s_and_b32 s33, s2, 7
	s_lshl_b32 s33, s33, 11
	s_addk_i32 s33, 0x7ff
	s_cmpk_eq_u32 s92, 0x100
	s_cselect_b32 s33, s33, 0x3fff
	v_cvt_pk_bf16_f32 v16, v16, v17
	v_cvt_pk_bf16_f32 v17, v18, v19
	global_store_dwordx2 v[30:31], v[16:17], off offset:-2560
	ds_read_b128 v[16:19], v54 offset:20480
	ds_read_b128 v[20:23], v54 offset:36864
	v_cmp_lt_i32_e32 vcc, s33, v32
	v_lshl_add_u64 v[36:37], v[36:37], 0, s[26:27]
	s_or_b64 s[30:31], vcc, s[30:31]
	s_waitcnt lgkmcnt(0)
	v_pk_fma_f32 v[14:15], v[18:19], v[14:15], v[22:23]
	v_pk_fma_f32 v[12:13], v[16:17], v[12:13], v[20:21]
	s_nop 0
	v_cvt_pk_bf16_f32 v12, v12, v13
	v_cvt_pk_bf16_f32 v13, v14, v15
	global_store_dwordx2 v[30:31], v[12:13], off offset:-2048
	ds_read_b128 v[12:15], v54 offset:21504
	ds_read_b128 v[16:19], v54 offset:37888
	s_waitcnt lgkmcnt(0)
	v_pk_fma_f32 v[10:11], v[14:15], v[10:11], v[18:19]
	v_pk_fma_f32 v[8:9], v[12:13], v[8:9], v[16:17]
	s_nop 0
	v_cvt_pk_bf16_f32 v8, v8, v9
	v_cvt_pk_bf16_f32 v9, v10, v11
	global_store_dwordx2 v[30:31], v[8:9], off offset:-1536
	ds_read_b128 v[8:11], v54 offset:22528
	ds_read_b128 v[12:15], v54 offset:38912
	s_waitcnt lgkmcnt(0)
	v_pk_fma_f32 v[6:7], v[10:11], v[6:7], v[14:15]
	v_pk_fma_f32 v[4:5], v[8:9], v[4:5], v[12:13]
	s_nop 0
	v_cvt_pk_bf16_f32 v4, v4, v5
	v_cvt_pk_bf16_f32 v5, v6, v7
	global_store_dwordx2 v[30:31], v[4:5], off offset:-1024
	ds_read_b128 v[4:7], v54 offset:23552
	ds_read_b128 v[8:11], v54 offset:39936
	s_waitcnt lgkmcnt(0)
	v_pk_fma_f32 v[2:3], v[6:7], v[2:3], v[10:11]
	v_pk_fma_f32 v[0:1], v[4:5], v[0:1], v[8:9]
	s_nop 0
	v_cvt_pk_bf16_f32 v0, v0, v1
	v_cvt_pk_bf16_f32 v1, v2, v3
	global_store_dwordx2 v[30:31], v[0:1], off offset:-512
	s_andn2_b64 exec, exec, s[30:31]
	s_cbranch_execnz .LBB0_803

; #define PG8_STAGE(bufoff, gbase, voff) do { _Pragma("unroll") for (int _i = 0; _i < 2; ++_i) \
;         __builtin_amdgcn_global_load_lds((const unsigned*)((const char*)(gbase) + (voff)[_i]), (PG8_LAS unsigned*)(lds + (bufoff) + ldsw + _i * 8192), 16, 0, 0); } while (0)
; #define PG8_WAIT_V(n) asm volatile("s_waitcnt vmcnt(" #n ")" ::: "memory")
; #define PG8_BAR __builtin_amdgcn_s_barrier()
; template <class Epi, class Sched, bool ALIGN_EPI = false, bool SP2 = false>
; __device__ __forceinline__ void gemm_phase(PG8_LAS unsigned char* lds, const Gemm g, const Sched& S, const Epi& E) {
;     ...
;         PG8_STAGE(PG8_SB(0, 0), cB, voffB); PG8_STAGE(PG8_SB(0, 1), cB + hstepB, voffB); PG8_STAGE(PG8_SA(0, 0), cA, voffA); PG8_STAGE(PG8_SA(0, 1), cA + hstepA, voffA);
;         if (wr == 1) PG8_BAR;
;         PG8_WAIT_V(2); PG8_BAR;
;         PG8_STAGE(PG8_SB(1, 0), cB + kstep, voffB); PG8_STAGE(PG8_SA(1, 0), cA + kstep, voffA); PG8_STAGE(PG8_SB(1, 1), cB + hstepB + kstep, voffB);
;         PG8_WAIT_V(6); PG8_BAR;
.LBB0_860:
	v_lshrrev_b32_e32 v16, 1, v14
	v_and_b32_e32 v16, 24, v16
	v_and_b32_e32 v15, 15, v14
	v_lshlrev_b32_e32 v17, 1, v16
	v_lshlrev_b32_e32 v14, 2, v14
	s_sext_i32_i16 s70, s26
	v_lshl_or_b32 v144, s31, 6, v15
	v_lshl_or_b32 v15, v15, 6, v17
	s_lshl_b32 s26, s31, 13
	v_and_b32_e32 v14, 32, v14
	v_bitop3_b32 v17, v15, s26, v14 bitop3:0xde
	s_lshl_b32 s26, s27, 5
	s_and_b32 s36, s26, 0x60
	s_lshl_b32 s26, s36, 7
	v_bitop3_b32 v145, v15, s26, v14 bitop3:0xde
	s_mov_b64 s[26:27], 0x80
	s_add_i32 m0, s45, 0x18000
	v_lshl_add_u64 v[6:7], v[6:7], 0, s[26:27]
	global_load_lds_dwordx4 v[6:7], off
	v_lshl_add_u64 v[4:5], v[4:5], 0, s[26:27]
	s_add_i32 m0, s45, 0x1a000
	s_add_i32 s64, s45, 0x8000
	s_add_i32 s65, s45, 0xa000
	global_load_lds_dwordx4 v[4:5], off
	v_lshl_add_u64 v[0:1], v[0:1], 0, s[26:27]
	s_mov_b32 m0, s64
	s_add_u32 s34, s52, 0x80080
	global_load_lds_dwordx4 v[0:1], off
	v_lshl_add_u64 v[0:1], v[2:3], 0, s[26:27]
	s_mov_b32 m0, s65
	s_addc_u32 s35, s53, 0
	global_load_lds_dwordx4 v[0:1], off
	s_add_i32 m0, s45, 0x1c000
	v_lshl_add_u64 v[0:1], s[34:35], 0, v[132:133]
	global_load_lds_dwordx4 v[0:1], off
	v_lshl_add_u64 v[0:1], s[34:35], 0, v[128:129]
	s_add_i32 m0, s45, 0x1e000
	s_cmpk_lt_u32 s30, 0x100
	global_load_lds_dwordx4 v[0:1], off
	s_waitcnt vmcnt(8)
	s_barrier
	v_lshlrev_b32_e32 v0, 15, v12
	v_and_b32_e32 v0, 0xffff0000, v0
	v_lshl_add_u32 v0, v11, 12, v0
	v_and_b32_e32 v1, 1, v12
	v_lshl_or_b32 v0, v1, 6, v0
	v_lshl_add_u32 v136, v13, 1, v0
	v_lshlrev_b32_e32 v0, 15, v8
	v_and_b32_e32 v0, 0xffff0000, v0
	s_waitcnt vmcnt(6)
	v_lshl_add_u32 v0, v9, 12, v0
	v_and_b32_e32 v1, 1, v8
	s_cselect_b64 s[30:31], -1, 0
	v_lshl_or_b32 v0, v1, 6, v0
	s_add_i32 s67, 0, 0x10000
	s_add_i32 s68, 0, 0x14000
	s_ashr_i32 s66, s92, 31
	v_or_b32_e32 v146, s36, v16
	v_mov_b32_e32 v137, v133
	v_lshl_add_u32 v138, v10, 1, v0
	v_mov_b32_e32 v139, v133
	v_mov_b64_e32 v[140:141], 0xb00
	v_mov_b64_e32 v[142:143], 0xaff
	v_add_u32_e32 v147, s67, v145
	v_add_u32_e32 v148, s68, v145
	v_add_u32_e32 v149, 0, v17
	s_movk_i32 s69, 0x2c00
	s_barrier
	s_branch .LBB0_863

; #define PG8_STAGE(bufoff, gbase, voff) do { _Pragma("unroll") for (int _i = 0; _i < 2; ++_i) \
;         __builtin_amdgcn_global_load_lds((const unsigned*)((const char*)(gbase) + (voff)[_i]), (PG8_LAS unsigned*)(lds + (bufoff) + ldsw + _i * 8192), 16, 0, 0); } while (0)
; #define PG8_WAIT_V(n) asm volatile("s_waitcnt vmcnt(" #n ")" ::: "memory")
; #define PG8_BAR __builtin_amdgcn_s_barrier()
; template <class Epi, class Sched, bool ALIGN_EPI = false, bool SP2 = false>
; __device__ __forceinline__ void gemm_phase(PG8_LAS unsigned char* lds, const Gemm g, const Sched& S, const Epi& E) {
;     ...
;         PG8_STAGE(PG8_SB(0, 0), cB, voffB); PG8_STAGE(PG8_SB(0, 1), cB + hstepB, voffB); PG8_STAGE(PG8_SA(0, 0), cA, voffA); PG8_STAGE(PG8_SA(0, 1), cA + hstepA, voffA);
;         if (wr == 1) PG8_BAR;
;         PG8_WAIT_V(2); PG8_BAR;
;         PG8_STAGE(PG8_SB(1, 0), cB + kstep, voffB); PG8_STAGE(PG8_SA(1, 0), cA + kstep, voffA); PG8_STAGE(PG8_SB(1, 1), cB + hstepB + kstep, voffB);
;         PG8_WAIT_V(6); PG8_BAR;
.LBB0_932:
	v_lshrrev_b32_e32 v18, 1, v16
	v_and_b32_e32 v18, 24, v18
	v_and_b32_e32 v17, 15, v16
	v_lshlrev_b32_e32 v19, 1, v18
	v_lshlrev_b32_e32 v16, 2, v16
	s_lshl_b32 s1, s1, 5
	v_lshl_or_b32 v144, s26, 6, v17
	v_lshl_or_b32 v17, v17, 6, v19
	s_lshl_b32 s26, s26, 13
	v_and_b32_e32 v16, 32, v16
	s_and_b32 s1, s1, 0x60
	v_bitop3_b32 v19, v17, s26, v16 bitop3:0xde
	s_lshl_b32 s26, s1, 7
	s_sext_i32_i8 s62, s27
	v_bitop3_b32 v145, v17, s26, v16 bitop3:0xde
	s_mov_b64 s[26:27], 0x80
	s_add_i32 m0, s43, 0x18000
	v_lshl_add_u64 v[6:7], v[6:7], 0, s[26:27]
	global_load_lds_dwordx4 v[6:7], off
	v_lshl_add_u64 v[2:3], v[2:3], 0, s[26:27]
	s_add_i32 m0, s43, 0x1a000
	s_add_i32 s52, s43, 0x8000
	s_add_i32 s53, s43, 0xa000
	global_load_lds_dwordx4 v[2:3], off
	v_lshl_add_u64 v[0:1], v[0:1], 0, s[26:27]
	s_mov_b32 m0, s52
	s_add_u32 s40, s36, 0x160080
	global_load_lds_dwordx4 v[0:1], off
	v_lshl_add_u64 v[0:1], v[4:5], 0, s[26:27]
	s_mov_b32 m0, s53
	s_addc_u32 s41, s37, 0
	global_load_lds_dwordx4 v[0:1], off
	s_add_i32 m0, s43, 0x1c000
	v_lshl_add_u64 v[0:1], s[40:41], 0, v[130:131]
	global_load_lds_dwordx4 v[0:1], off
	v_lshl_add_u64 v[0:1], s[40:41], 0, v[134:135]
	s_add_i32 m0, s43, 0x1e000
	s_mov_b64 s[38:39], 0x160080
	global_load_lds_dwordx4 v[0:1], off
	s_waitcnt vmcnt(8)
	s_barrier
	v_lshrrev_b32_e32 v1, 1, v8
	v_mul_lo_u32 v0, v9, s0
	v_mad_u64_u32 v[0:1], s[40:41], v1, s30, v[0:1]
	v_or_b32_e32 v0, v0, v10
	v_add_lshl_u32 v0, v0, v11, 1
	v_mov_b32_e32 v1, v131
	v_lshl_add_u64 v[136:137], v[0:1], 0, s[38:39]
	v_lshrrev_b32_e32 v1, 1, v12
	v_mul_lo_u32 v0, v13, s0
	v_or_b32_e32 v146, s1, v18
	v_mad_u64_u32 v[0:1], s[0:1], v1, s30, v[0:1]
	s_waitcnt vmcnt(6)
	s_cmpk_lt_u32 s28, 0x100
	v_or_b32_e32 v0, v0, v14
	s_cselect_b64 s[28:29], -1, 0
	v_add_lshl_u32 v0, v0, v15, 1
	v_mov_b32_e32 v1, v131
	s_add_i32 s60, 0, 0x10000
	s_add_i32 s61, 0, 0x14000
	s_ashr_i32 s54, s92, 31
	v_lshl_add_u64 v[138:139], v[0:1], 0, s[38:39]
	v_mov_b64_e32 v[140:141], 0x200
	v_mov_b64_e32 v[142:143], 0x1ff
	v_add_u32_e32 v147, s60, v145
	v_add_u32_e32 v148, s61, v145
	v_add_u32_e32 v149, 0, v19
	s_barrier
	s_branch .LBB0_935

; __device__ __forceinline__ void p10_rows(const Params& P, LAS unsigned char* lds, int G) {
;     ...
;     for (int m = blockIdx.x * 8 + wave; m < M; m += G * 8) {
;         const int b = m >> 13; const u32x2* fr = (const u32x2*)(F + (size_t)m * DM) + lane; f32x4* outr = (f32x4*)(P.out + (size_t)m * DM) + lane; const u32x2* x1r = (const u32x2*)((const bf16_t*)(P.ws + WS_X1) + (size_t)m * DM) + lane;
;         f32x4 v[8]; u32x2 xw8[8]; float ss = 0.f;
; #pragma unroll
;         for (int j = 0; j < 8; ++j) xw8[j] = __builtin_nontemporal_load(x1r + 64 * j);
; #pragma unroll
;         for (int j = 0; j < 8; ++j) { const u32x2 w = __builtin_nontemporal_load(fr + 64 * j); v[j][0] = __uint_as_float(w.x << 16); v[j][1] = __uint_as_float(w.x & 0xffff0000u); v[j][2] = __uint_as_float(w.y << 16); v[j][3] = __uint_as_float(w.y & 0xffff0000u);
;             ss += (v[j][0] * v[j][0] + v[j][1] * v[j][1]) + (v[j][2] * v[j][2] + v[j][3] * v[j][3]); }
.LBB0_1021:
	v_add_co_u32_e32 v22, vcc, 0xf0800000, v2
	global_load_dwordx2 v[20:21], v[2:3], off nt
	global_load_dwordx2 v[18:19], v[2:3], off offset:512 nt
	global_load_dwordx2 v[16:17], v[2:3], off offset:1024 nt
	global_load_dwordx2 v[14:15], v[2:3], off offset:1536 nt
	global_load_dwordx2 v[12:13], v[2:3], off offset:2048 nt
	global_load_dwordx2 v[10:11], v[2:3], off offset:2560 nt
	global_load_dwordx2 v[8:9], v[2:3], off offset:3072 nt
	global_load_dwordx2 v[6:7], v[2:3], off offset:3584 nt
	v_addc_co_u32_e32 v23, vcc, -1, v3, vcc
	v_and_b32_e32 v31, 0xffffe000, v0
	v_add_co_u32_e32 v64, vcc, s10, v2
	global_load_dwordx2 v[22:23], v[22:23], off nt
	v_add_u32_e32 v31, v30, v31
	v_addc_co_u32_e32 v65, vcc, -1, v3, vcc
	ds_read_b128 v[32:35], v31
	ds_read_b128 v[36:39], v31 offset:1024
	ds_read_b128 v[40:43], v31 offset:2048
	ds_read_b128 v[44:47], v31 offset:3072
	ds_read_b128 v[48:51], v31 offset:4096
	ds_read_b128 v[52:55], v31 offset:5120
	ds_read_b128 v[56:59], v31 offset:6144
	ds_read_b128 v[60:63], v31 offset:7168
	global_load_dwordx2 v[66:67], v[64:65], off offset:-3584 nt
	global_load_dwordx2 v[68:69], v[64:65], off offset:-3072 nt
	global_load_dwordx2 v[70:71], v[64:65], off offset:-2560 nt
	global_load_dwordx2 v[72:73], v[64:65], off offset:-2048 nt
	global_load_dwordx2 v[74:75], v[64:65], off offset:-1536 nt
	global_load_dwordx2 v[76:77], v[64:65], off offset:-1024 nt
	global_load_dwordx2 v[78:79], v[64:65], off offset:-512 nt
	v_add_u32_e32 v0, s42, v0
	v_cmp_lt_i32_e64 s[0:1], s12, v0
	v_lshl_add_u64 v[2:3], v[2:3], 0, s[4:5]
	s_or_b64 s[8:9], s[0:1], s[8:9]
	s_waitcnt vmcnt(15)
	v_lshlrev_b32_e32 v64, 16, v20
	v_and_b32_e32 v65, 0xffff0000, v20
	v_lshlrev_b32_e32 v20, 16, v21
	s_waitcnt vmcnt(12)
	v_lshlrev_b32_e32 v84, 16, v14
	v_and_b32_e32 v85, 0xffff0000, v14
	v_lshlrev_b32_e32 v86, 16, v15
	s_waitcnt vmcnt(9)
	v_lshlrev_b32_e32 v98, 16, v9
	v_and_b32_e32 v99, 0xffff0000, v9
	s_waitcnt vmcnt(8)
	v_lshlrev_b32_e32 v102, 16, v7
	v_and_b32_e32 v103, 0xffff0000, v7
	v_and_b32_e32 v87, 0xffff0000, v15
	v_lshlrev_b32_e32 v88, 16, v12
	v_and_b32_e32 v89, 0xffff0000, v12
	s_waitcnt vmcnt(7)
	v_and_b32_e32 v7, 0xffff0000, v22
	v_and_b32_e32 v9, 0xffff0000, v23
	v_lshlrev_b32_e32 v90, 16, v13
	v_and_b32_e32 v91, 0xffff0000, v13
	v_lshlrev_b32_e32 v92, 16, v10
	v_and_b32_e32 v93, 0xffff0000, v10
	v_lshlrev_b32_e32 v94, 16, v11
	v_and_b32_e32 v95, 0xffff0000, v11
	v_lshlrev_b32_e32 v96, 16, v8
	v_and_b32_e32 v97, 0xffff0000, v8
	v_lshlrev_b32_e32 v100, 16, v6
	v_and_b32_e32 v101, 0xffff0000, v6
	v_lshlrev_b32_e32 v6, 16, v22
	v_lshlrev_b32_e32 v8, 16, v23
	v_mul_f32_e32 v10, v9, v9
	s_waitcnt vmcnt(6)
	v_lshlrev_b32_e32 v13, 16, v67
	v_lshlrev_b32_e32 v12, 16, v66
	v_and_b32_e32 v15, 0xffff0000, v67
	v_and_b32_e32 v14, 0xffff0000, v66
	s_waitcnt vmcnt(5)
	v_lshlrev_b32_e32 v22, 16, v68
	v_and_b32_e32 v23, 0xffff0000, v68
	v_lshlrev_b32_e32 v66, 16, v69
	v_and_b32_e32 v67, 0xffff0000, v69
	s_waitcnt vmcnt(4)
	v_lshlrev_b32_e32 v11, 16, v70
	v_and_b32_e32 v69, 0xffff0000, v70
	v_mul_f32_e32 v68, v7, v7
	s_waitcnt vmcnt(0)
; #define LAS __attribute__((address_space(3)))
; __device__ __forceinline__ void p10_rows(const Params& P, LAS unsigned char* lds, int G) {
;     ...
;         for (int j = 0; j < 8; ++j) { const u32x2 w = __builtin_nontemporal_load(fr + 64 * j); v[j][0] = __uint_as_float(w.x << 16); v[j][1] = __uint_as_float(w.x & 0xffff0000u); v[j][2] = __uint_as_float(w.y << 16); v[j][3] = __uint_as_float(w.y & 0xffff0000u);
;             ss += (v[j][0] * v[j][0] + v[j][1] * v[j][1]) + (v[j][2] * v[j][2] + v[j][3] * v[j][3]); }
;         const float rstd = rsqrtf(wave_sum(ss) * (1.0f / DM) + RMS_EPS);
; #pragma unroll
;         for (int j = 0; j < 8; ++j) { const f32x4 a = *(const LAS f32x4*)(TA + b * DM + 256 * j + 4 * lane); const u32x2 xw = xw8[j]; f32x4 x1; x1[0] = __uint_as_float(xw.x << 16); x1[1] = __uint_as_float(xw.x & 0xffff0000u); x1[2] = __uint_as_float(xw.y << 16); x1[3] = __uint_as_float(xw.y & 0xffff0000u); __builtin_nontemporal_store(x1 + v[j] * rstd * a, outr + 64 * j); }
	v_lshlrev_b32_e32 v111, 16, v78
	v_pk_fma_f32 v[114:115], v[8:9], v[8:9], v[10:11] op_sel_hi:[1,1,0]
	v_pk_mul_f32 v[116:117], v[14:15], v[14:15]
	v_pk_fma_f32 v[118:119], v[6:7], v[6:7], v[68:69] op_sel_hi:[1,1,0]
	v_lshlrev_b32_e32 v70, 16, v71
	v_and_b32_e32 v71, 0xffff0000, v71
	v_mov_b32_e32 v121, v11
	v_mul_f32_e32 v110, v23, v23
	v_mul_f32_e32 v122, v67, v67
	v_mov_b32_e32 v123, v111
	v_mov_b32_e32 v132, v12
	v_mov_b32_e32 v133, v14
	v_mov_b32_e32 v14, v13
	v_pk_fma_f32 v[12:13], v[12:13], v[12:13], v[116:117]
	v_mov_b32_e32 v10, v118
	v_mov_b32_e32 v120, v114
	v_mul_f32_e32 v31, v69, v69
	v_mul_f32_e32 v129, v70, v70
	v_mul_f32_e32 v131, v71, v71
	v_mov_b32_e32 v68, v11
	v_pk_add_f32 v[114:115], v[118:119], v[114:115]
	v_pk_fma_f32 v[116:117], v[22:23], v[22:23], v[110:111] op_sel_hi:[1,1,0]
	v_pk_fma_f32 v[118:119], v[66:67], v[66:67], v[122:123] op_sel_hi:[1,1,0]
	v_pk_mul_f32 v[10:11], v[10:11], v[120:121]
	v_pk_add_f32 v[12:13], v[12:13], v[12:13] op_sel:[0,1] op_sel_hi:[1,0]
	v_lshlrev_b32_e32 v105, 16, v73
	v_lshlrev_b32_e32 v104, 16, v72
	v_and_b32_e32 v73, 0xffff0000, v73
	v_and_b32_e32 v72, 0xffff0000, v72
	v_mov_b32_e32 v117, v129
	v_mov_b32_e32 v119, v131
	v_mov_b32_e32 v115, v11
	v_mov_b32_e32 v13, v31
	v_pk_mul_f32 v[124:125], v[72:73], v[72:73]
	v_pk_add_f32 v[10:11], v[116:117], v[118:119]
	v_pk_add_f32 v[12:13], v[114:115], v[12:13]
	v_lshlrev_b32_e32 v107, 16, v75
	v_lshlrev_b32_e32 v106, 16, v74
	v_and_b32_e32 v75, 0xffff0000, v75
	v_and_b32_e32 v74, 0xffff0000, v74
	v_mov_b32_e32 v134, v104
	v_mov_b32_e32 v135, v72
	v_mov_b32_e32 v72, v105
	v_pk_fma_f32 v[104:105], v[104:105], v[104:105], v[124:125]
	v_pk_add_f32 v[10:11], v[12:13], v[10:11]
	v_lshlrev_b32_e32 v108, 16, v76
	v_and_b32_e32 v109, 0xffff0000, v76
	v_lshlrev_b32_e32 v76, 16, v77
	v_and_b32_e32 v77, 0xffff0000, v77
	v_pk_mul_f32 v[126:127], v[74:75], v[74:75]
	v_pk_add_f32 v[104:105], v[104:105], v[104:105] op_sel:[0,1] op_sel_hi:[1,0]
	v_pk_add_f32 v[10:11], v[10:11], v[10:11] op_sel:[0,1] op_sel_hi:[1,0]
	v_and_b32_e32 v113, 0xffff0000, v78
	v_lshlrev_b32_e32 v78, 16, v79
	v_and_b32_e32 v79, 0xffff0000, v79
	v_mul_f32_e32 v128, v109, v109
	v_mul_f32_e32 v130, v77, v77
	v_mov_b32_e32 v136, v106
	v_mov_b32_e32 v137, v74
	v_mov_b32_e32 v74, v107
	v_pk_fma_f32 v[106:107], v[106:107], v[106:107], v[126:127]
	v_mov_b32_e32 v122, v104
	v_mov_b32_e32 v110, v10
	v_mul_f32_e32 v138, v113, v113
	v_mul_f32_e32 v139, v78, v78
	v_mul_f32_e32 v140, v79, v79
	v_pk_fma_f32 v[124:125], v[108:109], v[108:109], v[128:129] op_sel_hi:[1,1,0]
	v_pk_fma_f32 v[126:127], v[76:77], v[76:77], v[130:131] op_sel_hi:[1,1,0]
	v_pk_add_f32 v[106:107], v[106:107], v[106:107] op_sel:[0,1] op_sel_hi:[1,0]
	v_pk_add_f32 v[10:11], v[10:11], v[104:105]
	v_pk_mul_f32 v[12:13], v[110:111], v[122:123]
	v_mov_b32_e32 v125, v139
	v_mov_b32_e32 v127, v140
	v_mov_b32_e32 v107, v138
	v_mov_b32_e32 v11, v13
	v_pk_add_f32 v[116:117], v[124:125], v[126:127]
	v_pk_add_f32 v[10:11], v[10:11], v[106:107]
	v_and_b32_e32 v21, 0xffff0000, v21
	v_pk_add_f32 v[10:11], v[10:11], v[116:117]
	v_mov_b32_e32 v112, v111
	v_add_f32_e32 v10, v10, v11
	s_nop 1
	v_add_f32_dpp v10, v10, v10 quad_perm:[1,0,3,2] row_mask:0xf bank_mask:0xf
	v_lshlrev_b32_e32 v80, 16, v18
	v_and_b32_e32 v81, 0xffff0000, v18
	v_lshlrev_b32_e32 v18, 16, v19
	v_and_b32_e32 v19, 0xffff0000, v19
	s_nop 1
	v_add_f32_dpp v10, v10, v10 quad_perm:[2,3,0,1] row_mask:0xf bank_mask:0xf
	v_lshlrev_b32_e32 v82, 16, v16
	v_and_b32_e32 v83, 0xffff0000, v16
	v_lshlrev_b32_e32 v16, 16, v17
	v_and_b32_e32 v17, 0xffff0000, v17
	s_nop 1
	v_add_f32_dpp v10, v10, v10 row_half_mirror row_mask:0xf bank_mask:0xf
	s_nop 1
	v_add_f32_dpp v10, v10, v10 row_mirror row_mask:0xf bank_mask:0xf
	v_mov_b32_e32 v11, v10
	s_nop 1
	v_permlane16_swap_b32_e32 v11, v10
	v_add_f32_e32 v10, v10, v11
	v_mov_b32_e32 v11, v10
	s_nop 1
	v_permlane32_swap_b32_e32 v11, v10
	v_add_f32_e32 v10, v10, v11
	s_waitcnt lgkmcnt(0)
	v_fmamk_f32 v10, v10, 0x3a000000, v1
	v_mul_f32_e32 v11, 0x4b800000, v10
	v_cmp_gt_f32_e32 vcc, s11, v10
	s_nop 1
	v_cndmask_b32_e32 v10, v10, v11, vcc
	v_rsq_f32_e32 v10, v10
	s_nop 0
	v_mul_f32_e32 v11, 0x45800000, v10
	v_cndmask_b32_e32 v10, v10, v11, vcc
	v_pk_mul_f32 v[6:7], v[10:11], v[6:7] op_sel_hi:[0,1]
	v_pk_mul_f32 v[8:9], v[10:11], v[8:9] op_sel_hi:[0,1]
	v_pk_mul_f32 v[104:105], v[10:11], v[132:133] op_sel_hi:[0,1]
	v_pk_mul_f32 v[12:13], v[10:11], v[14:15] op_sel_hi:[0,1]
	v_pk_mul_f32 v[14:15], v[10:11], v[22:23] op_sel_hi:[0,1]
	v_pk_mul_f32 v[22:23], v[10:11], v[66:67] op_sel_hi:[0,1]
	v_pk_mul_f32 v[66:67], v[68:69], v[10:11] op_sel_hi:[1,0]
	v_pk_mul_f32 v[68:69], v[70:71], v[10:11] op_sel_hi:[1,0]
	v_pk_mul_f32 v[70:71], v[10:11], v[134:135] op_sel_hi:[0,1]
	v_pk_mul_f32 v[72:73], v[10:11], v[72:73] op_sel_hi:[0,1]
	v_pk_mul_f32 v[106:107], v[10:11], v[136:137] op_sel_hi:[0,1]
	v_pk_mul_f32 v[74:75], v[10:11], v[74:75] op_sel_hi:[0,1]
	v_pk_mul_f32 v[108:109], v[10:11], v[108:109] op_sel_hi:[0,1]
	v_pk_mul_f32 v[76:77], v[10:11], v[76:77] op_sel_hi:[0,1]
	v_pk_mul_f32 v[110:111], v[112:113], v[10:11] op_sel_hi:[1,0]
	v_pk_mul_f32 v[78:79], v[78:79], v[10:11] op_sel_hi:[1,0]
	v_pk_fma_f32 v[8:9], v[34:35], v[8:9], v[20:21]
	v_pk_fma_f32 v[6:7], v[32:33], v[6:7], v[64:65]
	v_pk_fma_f32 v[12:13], v[38:39], v[12:13], v[18:19]
	v_pk_fma_f32 v[10:11], v[36:37], v[104:105], v[80:81]
	v_pk_fma_f32 v[16:17], v[42:43], v[22:23], v[16:17]
	v_pk_fma_f32 v[14:15], v[40:41], v[14:15], v[82:83]
	v_pk_fma_f32 v[20:21], v[46:47], v[68:69], v[86:87]
	v_pk_fma_f32 v[18:19], v[44:45], v[66:67], v[84:85]
	v_pk_fma_f32 v[34:35], v[50:51], v[72:73], v[90:91]
	v_pk_fma_f32 v[32:33], v[48:49], v[70:71], v[88:89]
	v_pk_fma_f32 v[38:39], v[54:55], v[74:75], v[94:95]
	v_pk_fma_f32 v[36:37], v[52:53], v[106:107], v[92:93]
	v_pk_fma_f32 v[42:43], v[58:59], v[76:77], v[98:99]
	v_pk_fma_f32 v[40:41], v[56:57], v[108:109], v[96:97]
	v_pk_fma_f32 v[46:47], v[62:63], v[78:79], v[102:103]
	v_pk_fma_f32 v[44:45], v[60:61], v[110:111], v[100:101]
	global_store_dwordx4 v[4:5], v[6:9], off offset:-4096 nt
	global_store_dwordx4 v[4:5], v[10:13], off offset:-3072 nt
	global_store_dwordx4 v[4:5], v[14:17], off offset:-2048 nt
	global_store_dwordx4 v[4:5], v[18:21], off offset:-1024 nt
	global_store_dwordx4 v[4:5], v[32:35], off nt
	global_store_dwordx4 v[4:5], v[36:39], off offset:1024 nt
	global_store_dwordx4 v[4:5], v[40:43], off offset:2048 nt
	global_store_dwordx4 v[4:5], v[44:47], off offset:3072 nt
	v_lshl_add_u64 v[4:5], v[4:5], 0, s[6:7]
	s_andn2_b64 exec, exec, s[8:9]
	s_cbranch_execnz .LBB0_1021
